# attention prompt tiles: output accumulators stay in place (32 v_mov_b64 per tile removed), PV MFMAs accumulate into v[4:35]
# speedup vs baseline: 1.0059x; 1.0004x over previous
.LBB0_1416:
	v_lshrrev_b32_e32 v3, s42, v159
	v_and_b32_e32 v3, 1, v3
	v_cmp_eq_u32_e64 s[2:3], 1, v3
	s_or_b64 s[8:9], s[28:29], s[2:3]
	v_cndmask_b32_e64 v3, 0, 1, s[8:9]
	v_cmp_ne_u32_e32 vcc, 0, v3
	s_cbranch_vccz .LBB0_1443
	s_cmp_lt_i32 s42, s48
	s_cselect_b64 s[24:25], -1, 0
	s_cmp_ge_i32 s42, s48
	s_cselect_b64 s[30:31], -1, 0
	s_mov_b64 s[26:27], -1
	s_and_b64 vcc, exec, s[20:21]
	v_lshl_or_b32 v165, s42, 6, v136
	s_cbranch_vccz .LBB0_1426
	v_sub_u32_e32 v68, v161, v165
	v_cvt_f32_i32_e32 v221, v68
	v_add_u32_e32 v219, s38, v176
	s_and_b64 vcc, exec, s[30:31]
	v_add_u32_e32 v69, v219, v177
	v_add_u32_e32 v220, v219, v178
	s_cbranch_vccz .LBB0_1422
	v_mov_b32_e32 v3, v157
	ds_read_b128 v[52:55], v69
	ds_read_b128 v[56:59], v69 offset:32
	v_mul_f32_e64 v36, v221, -v3
	v_cndmask_b32_e64 v66, v214, v36, s[2:3]
	v_mov_b32_e32 v74, v3
	v_fma_f32 v38, 0, v3, v66
	v_fmamk_f32 v42, v3, 0x41000000, v66
	v_fmamk_f32 v46, v3, 0x41800000, v66
	v_fmamk_f32 v50, v3, 0x41c00000, v66
	v_pk_add_f32 v[36:37], v[2:3], v[38:39] op_sel_hi:[1,0]
	v_pk_fma_f32 v[38:39], v[74:75], s[64:65], v[38:39] op_sel_hi:[0,1,0]
	v_pk_add_f32 v[40:41], v[2:3], v[42:43] op_sel_hi:[1,0]
	v_pk_fma_f32 v[42:43], v[74:75], s[64:65], v[42:43] op_sel_hi:[0,1,0]
	v_pk_add_f32 v[44:45], v[2:3], v[46:47] op_sel_hi:[1,0]
	v_pk_fma_f32 v[46:47], v[74:75], s[64:65], v[46:47] op_sel_hi:[0,1,0]
	v_pk_add_f32 v[48:49], v[2:3], v[50:51] op_sel_hi:[1,0]
	v_pk_fma_f32 v[50:51], v[74:75], s[64:65], v[50:51] op_sel_hi:[0,1,0]
	v_fmamk_f32 v62, v3, 0x42200000, v66
	v_fmamk_f32 v64, v3, 0x42400000, v66
	s_waitcnt lgkmcnt(1)
	v_mfma_f32_32x32x16_bf16 v[36:51], v[52:55], v[100:103], v[36:51]
	v_cmp_lt_i32_e32 vcc, -1, v68
	s_waitcnt lgkmcnt(0)
	v_mfma_f32_32x32x16_bf16 v[36:51], v[56:59], v[104:107], v[36:51]
	ds_read_b128 v[52:55], v69 offset:64
	ds_read_b128 v[58:61], v69 offset:96
	ds_read_b128 v[70:73], v220
	v_add_f32_e64 v56, v2, v62
	v_add_f32_e64 v57, v3, v62
	s_waitcnt lgkmcnt(2)
	v_mfma_f32_32x32x16_bf16 v[36:51], v[52:55], v[108:111], v[36:51]
	v_fmamk_f32 v54, v3, 0x42000000, v66
	v_fmac_f32_e32 v66, 0x42600000, v3
	v_add_f32_e64 v52, v2, v54
	v_add_f32_e64 v53, v3, v54
	v_pk_fma_f32 v[54:55], v[74:75], s[64:65], v[54:55] op_sel_hi:[0,1,0]
	s_waitcnt lgkmcnt(1)
	v_mfma_f32_32x32x16_bf16 v[36:51], v[58:61], v[112:115], v[36:51]
	v_fma_f32 v58, v74, s64, v62
	v_fma_f32 v59, v74, s65, v62
	v_add_f32_e64 v60, v2, v64
	v_add_f32_e64 v61, v3, v64
	v_fma_f32 v62, v74, s64, v64
	v_fma_f32 v63, v74, s65, v64
	v_pk_add_f32 v[64:65], v[2:3], v[66:67] op_sel_hi:[1,0]
	v_pk_fma_f32 v[66:67], v[74:75], s[64:65], v[66:67] op_sel_hi:[0,1,0]
	ds_read_b128 v[74:77], v220 offset:32
	s_nop 2
	v_cndmask_b32_e32 v86, v214, v36, vcc
	s_waitcnt lgkmcnt(1)
	v_mfma_f32_32x32x16_bf16 v[52:67], v[70:73], v[100:103], v[52:67]
	ds_read_b128 v[70:73], v220 offset:64
	ds_read_b128 v[78:81], v220 offset:96
	v_cmp_lt_i32_e32 vcc, 0, v68
	s_nop 1
	v_cndmask_b32_e32 v87, v214, v37, vcc
	v_cmp_lt_i32_e32 vcc, 1, v68
	v_max3_f32 v3, v86, s97, v87
	s_waitcnt lgkmcnt(2)
	v_mfma_f32_32x32x16_bf16 v[52:67], v[74:77], v[104:107], v[52:67]
	v_cndmask_b32_e32 v94, v214, v38, vcc
	v_cmp_lt_i32_e32 vcc, 2, v68
	s_nop 1
	v_cndmask_b32_e32 v95, v214, v39, vcc
	v_cmp_lt_i32_e32 vcc, 7, v68
	v_max3_f32 v3, v3, v94, v95
	s_waitcnt lgkmcnt(1)
	v_mfma_f32_32x32x16_bf16 v[52:67], v[70:73], v[108:111], v[52:67]
	v_cndmask_b32_e32 v98, v214, v40, vcc
	v_cmp_lt_i32_e32 vcc, 8, v68
	s_nop 1
	v_cndmask_b32_e32 v99, v214, v41, vcc
	v_cmp_lt_i32_e32 vcc, 9, v68
	v_max3_f32 v3, v3, v98, v99
	s_waitcnt lgkmcnt(0)
	v_mfma_f32_32x32x16_bf16 v[52:67], v[78:81], v[112:115], v[52:67]
	v_cndmask_b32_e32 v96, v214, v42, vcc
	v_cmp_lt_i32_e32 vcc, 10, v68
	s_nop 1
	v_cndmask_b32_e32 v97, v214, v43, vcc
	v_cmp_lt_i32_e32 vcc, 15, v68
	v_max3_f32 v3, v3, v96, v97
	s_nop 0
	v_cndmask_b32_e32 v170, v214, v44, vcc
	v_cmp_lt_i32_e32 vcc, 16, v68
	s_nop 1
	v_cndmask_b32_e32 v171, v214, v45, vcc
	v_cmp_lt_i32_e32 vcc, 17, v68
	v_max3_f32 v3, v3, v170, v171
	s_nop 0
	v_cndmask_b32_e32 v90, v214, v46, vcc
	v_cmp_lt_i32_e32 vcc, 18, v68
	s_nop 1
	v_cndmask_b32_e32 v91, v214, v47, vcc
	v_cmp_lt_i32_e32 vcc, 23, v68
	v_max3_f32 v3, v3, v90, v91
	s_nop 0
	v_cndmask_b32_e32 v92, v214, v48, vcc
	v_cmp_lt_i32_e32 vcc, 24, v68
	s_nop 1
	v_cndmask_b32_e32 v93, v214, v49, vcc
	v_cmp_lt_i32_e32 vcc, 25, v68
	v_max3_f32 v3, v3, v92, v93
	s_nop 0
	v_cndmask_b32_e32 v88, v214, v50, vcc
	v_cmp_lt_i32_e32 vcc, 26, v68
	s_nop 1
	v_cndmask_b32_e32 v89, v214, v51, vcc
	v_cmp_lt_i32_e32 vcc, 31, v68
	v_max3_f32 v3, v3, v88, v89
	s_nop 0
	v_cndmask_b32_e32 v84, v214, v52, vcc
	v_cmp_lt_i32_e32 vcc, 32, v68
	s_nop 1
	v_cndmask_b32_e32 v85, v214, v53, vcc
	v_cmp_lt_i32_e32 vcc, 33, v68
	v_max3_f32 v3, v3, v84, v85
	s_nop 0
	v_cndmask_b32_e32 v82, v214, v54, vcc
	v_cmp_lt_i32_e32 vcc, 34, v68
	s_nop 1
	v_cndmask_b32_e32 v83, v214, v55, vcc
	v_cmp_lt_i32_e32 vcc, 39, v68
	v_max3_f32 v3, v3, v82, v83
	s_nop 0
	v_cndmask_b32_e32 v80, v214, v56, vcc
	v_cmp_lt_i32_e32 vcc, 40, v68
	s_nop 1
	v_cndmask_b32_e32 v81, v214, v57, vcc
	v_cmp_lt_i32_e32 vcc, 41, v68
	v_max3_f32 v3, v3, v80, v81
	s_nop 0
	v_cndmask_b32_e32 v78, v214, v58, vcc
	v_cmp_lt_i32_e32 vcc, 42, v68
	s_nop 1
	v_cndmask_b32_e32 v79, v214, v59, vcc
	v_cmp_lt_i32_e32 vcc, 47, v68
	v_max3_f32 v3, v3, v78, v79
	s_nop 0
	v_cndmask_b32_e32 v76, v214, v60, vcc
	v_cmp_lt_i32_e32 vcc, 48, v68
	s_nop 1
	v_cndmask_b32_e32 v77, v214, v61, vcc
	v_cmp_lt_i32_e32 vcc, 49, v68
	v_max3_f32 v3, v3, v76, v77
	s_nop 0
	v_cndmask_b32_e32 v74, v214, v62, vcc
	v_cmp_lt_i32_e32 vcc, 50, v68
	s_nop 1
	v_cndmask_b32_e32 v75, v214, v63, vcc
	v_cmp_lt_i32_e32 vcc, 55, v68
	v_max3_f32 v3, v3, v74, v75
	s_nop 0
	v_cndmask_b32_e32 v70, v214, v64, vcc
	v_cmp_lt_i32_e32 vcc, 56, v68
	s_nop 1
	v_cndmask_b32_e32 v71, v214, v65, vcc
	v_cmp_lt_i32_e32 vcc, 57, v68
	v_max3_f32 v3, v3, v70, v71
	s_nop 0
	v_cndmask_b32_e32 v72, v214, v66, vcc
	v_cmp_lt_i32_e32 vcc, 58, v68
	s_nop 1
	v_cndmask_b32_e32 v73, v214, v67, vcc
	v_max3_f32 v3, v3, v72, v73
	ds_bpermute_b32 v36, v179, v3
	s_nop 3
	s_waitcnt lgkmcnt(0)
	v_max_f32_e32 v36, v36, v36
	v_max_f32_e32 v3, v3, v36
	v_max3_f32 v132, v218, v3, s46
	v_sub_f32_e32 v3, v218, v132
	v_exp_f32_e32 v68, v3
	s_nop 2
	v_cmp_eq_f32_e32 vcc, 1.0, v68
	s_cmp_eq_u64 vcc, exec
	s_nop 8
	s_cbranch_scc1 .LBB0_1421
	v_pk_mul_f32 v[34:35], v[34:35], v[68:69] op_sel_hi:[1,0]
	v_pk_mul_f32 v[32:33], v[32:33], v[68:69] op_sel_hi:[1,0]
	v_pk_mul_f32 v[30:31], v[30:31], v[68:69] op_sel_hi:[1,0]
	v_pk_mul_f32 v[28:29], v[28:29], v[68:69] op_sel_hi:[1,0]
	v_pk_mul_f32 v[26:27], v[26:27], v[68:69] op_sel_hi:[1,0]
	v_pk_mul_f32 v[24:25], v[24:25], v[68:69] op_sel_hi:[1,0]
	v_pk_mul_f32 v[22:23], v[22:23], v[68:69] op_sel_hi:[1,0]
	v_pk_mul_f32 v[20:21], v[20:21], v[68:69] op_sel_hi:[1,0]
	v_pk_mul_f32 v[18:19], v[18:19], v[68:69] op_sel_hi:[1,0]
	v_pk_mul_f32 v[16:17], v[16:17], v[68:69] op_sel_hi:[1,0]
	v_pk_mul_f32 v[14:15], v[14:15], v[68:69] op_sel_hi:[1,0]
	v_pk_mul_f32 v[12:13], v[12:13], v[68:69] op_sel_hi:[1,0]
	v_pk_mul_f32 v[10:11], v[10:11], v[68:69] op_sel_hi:[1,0]
	v_pk_mul_f32 v[8:9], v[8:9], v[68:69] op_sel_hi:[1,0]
	v_pk_mul_f32 v[6:7], v[6:7], v[68:69] op_sel_hi:[1,0]
	v_pk_mul_f32 v[4:5], v[4:5], v[68:69] op_sel_hi:[1,0]
.LBB0_1421:
	v_pk_add_f32 v[94:95], v[94:95], v[132:133] op_sel_hi:[1,0] neg_lo:[0,1] neg_hi:[0,1]
	v_lshl_add_u32 v3, v136, 1, s38
	v_exp_f32_e32 v230, v94
	v_exp_f32_e32 v231, v95
	v_pk_add_f32 v[94:95], v[98:99], v[132:133] op_sel_hi:[1,0] neg_lo:[0,1] neg_hi:[0,1]
	v_pk_add_f32 v[86:87], v[86:87], v[132:133] op_sel_hi:[1,0] neg_lo:[0,1] neg_hi:[0,1]
	v_exp_f32_e32 v98, v94
	v_exp_f32_e32 v99, v95
	v_pk_add_f32 v[94:95], v[96:97], v[132:133] op_sel_hi:[1,0] neg_lo:[0,1] neg_hi:[0,1]
	v_exp_f32_e32 v86, v86
	v_exp_f32_e32 v232, v94
	v_add_u32_e32 v94, v3, v190
	v_add_u32_e32 v186, 0x2000, v94
	v_exp_f32_e32 v233, v95
	ds_read2_b64 v[94:97], v186 offset0:128 offset1:130
	v_add_u32_e32 v3, v3, v191
	v_add_u32_e32 v3, 0x2000, v3
	ds_read2_b64 v[226:229], v3 offset0:128 offset1:130
	v_exp_f32_e32 v87, v87
	v_pk_add_f32 v[90:91], v[90:91], v[132:133] op_sel_hi:[1,0] neg_lo:[0,1] neg_hi:[0,1]
	v_cvt_pk_bf16_f32 v223, v230, v231
	v_exp_f32_e32 v234, v90
	v_exp_f32_e32 v235, v91
	v_pk_add_f32 v[90:91], v[92:93], v[132:133] op_sel_hi:[1,0] neg_lo:[0,1] neg_hi:[0,1]
	v_cvt_pk_bf16_f32 v222, v86, v87
	v_cvt_pk_bf16_f32 v224, v98, v99
	v_cvt_pk_bf16_f32 v225, v232, v233
	v_exp_f32_e32 v236, v90
	v_exp_f32_e32 v237, v91
	ds_read2_b64 v[90:93], v186 offset0:132 offset1:134
	s_waitcnt lgkmcnt(2)
	v_mfma_f32_32x32x16_bf16 v[20:35], v[94:97], v[222:225], v[20:35]
	v_add_f32_e64 v170, v170, -v132
	v_add_f32_e64 v171, v171, -v132
	v_add_f32_e64 v88, v88, -v132
	v_add_f32_e64 v89, v89, -v132
	v_exp_f32_e32 v170, v170
	v_exp_f32_e32 v171, v171
	v_cvt_pk_bf16_f32 v95, v234, v235
	v_cvt_pk_bf16_f32 v96, v236, v237
	v_cvt_pk_bf16_f32 v94, v170, v171
	s_waitcnt lgkmcnt(1)
	v_mfma_f32_32x32x16_bf16 v[4:19], v[226:229], v[222:225], v[4:19]
	v_exp_f32_e32 v222, v88
	v_exp_f32_e32 v223, v89
	s_nop 0
	v_cvt_pk_bf16_f32 v97, v222, v223
	s_waitcnt lgkmcnt(0)
	s_nop 0
	v_mfma_f32_32x32x16_bf16 v[20:35], v[90:93], v[94:97], v[20:35]
	ds_read2_b64 v[88:91], v3 offset0:132 offset1:134
	s_waitcnt lgkmcnt(0)
	v_mfma_f32_32x32x16_bf16 v[4:19], v[88:91], v[94:97], v[4:19]
	v_add_f32_e64 v80, v80, -v132
	v_add_f32_e64 v81, v81, -v132
	v_add_f32_e64 v78, v78, -v132
	v_add_f32_e64 v79, v79, -v132
	v_exp_f32_e32 v94, v80
	v_exp_f32_e32 v95, v81
	v_exp_f32_e32 v96, v78
	v_exp_f32_e32 v97, v79
	v_pk_add_f32 v[80:81], v[76:77], v[132:133] op_sel_hi:[1,0] neg_lo:[0,1] neg_hi:[0,1]
	ds_read2_b64 v[76:79], v186 offset0:136 offset1:138
	v_pk_add_f32 v[84:85], v[84:85], v[132:133] op_sel_hi:[1,0] neg_lo:[0,1] neg_hi:[0,1]
	v_pk_add_f32 v[82:83], v[82:83], v[132:133] op_sel_hi:[1,0] neg_lo:[0,1] neg_hi:[0,1]
	ds_read2_b64 v[88:91], v3 offset0:136 offset1:138
	v_exp_f32_e32 v84, v84
	v_exp_f32_e32 v85, v85
	v_exp_f32_e32 v92, v82
	v_exp_f32_e32 v93, v83
	v_pk_add_f32 v[74:75], v[74:75], v[132:133] op_sel_hi:[1,0] neg_lo:[0,1] neg_hi:[0,1]
	v_pk_add_f32 v[70:71], v[70:71], v[132:133] op_sel_hi:[1,0] neg_lo:[0,1] neg_hi:[0,1]
	v_exp_f32_e32 v224, v80
	v_exp_f32_e32 v225, v81
	v_cvt_pk_bf16_f32 v80, v84, v85
	v_cvt_pk_bf16_f32 v81, v92, v93
	v_cvt_pk_bf16_f32 v82, v94, v95
	v_cvt_pk_bf16_f32 v83, v96, v97
	v_exp_f32_e32 v226, v74
	v_exp_f32_e32 v227, v75
	v_exp_f32_e32 v228, v70
	v_exp_f32_e32 v229, v71
	v_pk_add_f32 v[74:75], v[72:73], v[132:133] op_sel_hi:[1,0] neg_lo:[0,1] neg_hi:[0,1]
	ds_read2_b64 v[70:73], v186 offset0:140 offset1:142
	s_waitcnt lgkmcnt(2)
	v_mfma_f32_32x32x16_bf16 v[20:35], v[76:79], v[80:83], v[20:35]
	v_cvt_pk_bf16_f32 v78, v224, v225
	v_cvt_pk_bf16_f32 v79, v226, v227
	s_mov_b64 s[26:27], 0
	s_waitcnt lgkmcnt(1)
	v_mfma_f32_32x32x16_bf16 v[4:19], v[88:91], v[80:83], v[4:19]
	v_exp_f32_e32 v82, v74
	v_exp_f32_e32 v83, v75
	v_cvt_pk_bf16_f32 v80, v228, v229
	ds_read2_b64 v[74:77], v3 offset0:140 offset1:142
	v_cvt_pk_bf16_f32 v81, v82, v83
	s_waitcnt lgkmcnt(1)
	s_nop 0
	v_mfma_f32_32x32x16_bf16 v[20:35], v[70:73], v[78:81], v[20:35]
	v_add_f32_e64 v70, v86, 0
	v_add_f32_e64 v71, v87, 0
	v_add_f32_e64 v70, v230, v70
	v_add_f32_e64 v71, v231, v71
	v_add_f32_e64 v70, v98, v70
	v_add_f32_e64 v71, v99, v71
	v_pk_add_f32 v[70:71], v[232:233], v[70:71]
	s_waitcnt lgkmcnt(0)
	v_mfma_f32_32x32x16_bf16 v[4:19], v[74:77], v[78:81], v[4:19]
	v_add_f32_e64 v70, v170, v70
	v_add_f32_e64 v71, v171, v71
	v_add_f32_e64 v70, v234, v70
	v_add_f32_e64 v71, v235, v71
	v_add_f32_e64 v70, v236, v70
	v_add_f32_e64 v71, v237, v71
	v_pk_add_f32 v[70:71], v[222:223], v[70:71]
	s_nop 0
	v_pk_add_f32 v[70:71], v[84:85], v[70:71]
	s_nop 0
	v_pk_add_f32 v[70:71], v[92:93], v[70:71]
	s_nop 0
	v_pk_add_f32 v[70:71], v[94:95], v[70:71]
	s_nop 0
	v_pk_add_f32 v[70:71], v[96:97], v[70:71]
	s_nop 0
	v_pk_add_f32 v[70:71], v[224:225], v[70:71]
	s_nop 0
	v_pk_add_f32 v[70:71], v[226:227], v[70:71]
	s_nop 0
	v_pk_add_f32 v[70:71], v[228:229], v[70:71]
	s_nop 0
	v_pk_add_f32 v[70:71], v[82:83], v[70:71]
	s_nop 0
	v_add_f32_e32 v3, v70, v71
	ds_bpermute_b32 v70, v179, v3
	s_waitcnt lgkmcnt(0)
	v_add_f32_e32 v3, v3, v70
	v_fmac_f32_e32 v3, v217, v68
.LBB0_1422:
	s_and_b64 vcc, exec, s[26:27]
	s_cbranch_vccz .LBB0_1441
	v_mov_b32_e32 v3, v157
	s_nop 0
	v_mul_f32_e64 v36, v221, -v3
	v_cndmask_b32_e64 v44, v214, v36, s[2:3]
	v_mov_b32_e32 v46, v3
	v_fma_f32 v36, 0, v3, v44
	v_pk_add_f32 v[84:85], v[2:3], v[36:37] op_sel_hi:[1,0]
	v_pk_fma_f32 v[86:87], v[46:47], s[64:65], v[36:37] op_sel_hi:[0,1,0]
	ds_read_b128 v[36:39], v69
	v_fmamk_f32 v40, v3, 0x41000000, v44
	v_pk_add_f32 v[88:89], v[2:3], v[40:41] op_sel_hi:[1,0]
	v_pk_fma_f32 v[90:91], v[46:47], s[64:65], v[40:41] op_sel_hi:[0,1,0]
	v_fmamk_f32 v40, v3, 0x41800000, v44
	v_pk_add_f32 v[92:93], v[2:3], v[40:41] op_sel_hi:[1,0]
	v_pk_fma_f32 v[94:95], v[46:47], s[64:65], v[40:41] op_sel_hi:[0,1,0]
	v_fmamk_f32 v40, v3, 0x41c00000, v44
	v_pk_add_f32 v[96:97], v[2:3], v[40:41] op_sel_hi:[1,0]
	v_pk_fma_f32 v[98:99], v[46:47], s[64:65], v[40:41] op_sel_hi:[0,1,0]
	ds_read_b128 v[40:43], v69 offset:32
	v_fmamk_f32 v48, v3, 0x42000000, v44
	s_waitcnt lgkmcnt(1)
	v_mfma_f32_32x32x16_bf16 v[84:99], v[36:39], v[100:103], v[84:99]
	v_fmamk_f32 v50, v3, 0x42200000, v44
	v_fmamk_f32 v52, v3, 0x42400000, v44
	v_fmac_f32_e32 v44, 0x42600000, v3
	v_fma_f32 v70, v46, s64, v48
	v_fma_f32 v71, v46, s65, v48
	v_pk_add_f32 v[72:73], v[2:3], v[50:51] op_sel_hi:[1,0]
	v_pk_fma_f32 v[74:75], v[46:47], s[64:65], v[50:51] op_sel_hi:[0,1,0]
	v_pk_add_f32 v[76:77], v[2:3], v[52:53] op_sel_hi:[1,0]
	s_waitcnt lgkmcnt(0)
	v_mfma_f32_32x32x16_bf16 v[84:99], v[40:43], v[104:107], v[84:99]
	ds_read_b128 v[36:39], v69 offset:64
	ds_read_b128 v[40:43], v69 offset:96
	v_add_f32_e64 v68, v2, v48
	v_add_f32_e64 v69, v3, v48
	v_fma_f32 v78, v46, s64, v52
	v_fma_f32 v79, v46, s65, v52
	v_pk_add_f32 v[80:81], v[2:3], v[44:45] op_sel_hi:[1,0]
	v_pk_fma_f32 v[82:83], v[46:47], s[64:65], v[44:45] op_sel_hi:[0,1,0]
	s_nop 1
	s_waitcnt lgkmcnt(1)
	v_mfma_f32_32x32x16_bf16 v[84:99], v[36:39], v[108:111], v[84:99]
	ds_read_b128 v[36:39], v220
	s_nop 5
	s_waitcnt lgkmcnt(1)
	v_mfma_f32_32x32x16_bf16 v[84:99], v[40:43], v[112:115], v[84:99]
	ds_read_b128 v[40:43], v220 offset:32
	s_waitcnt lgkmcnt(1)
	v_mfma_f32_32x32x16_bf16 v[68:83], v[36:39], v[100:103], v[68:83]
	s_nop 8
	v_max3_f32 v3, v84, s97, v85
	v_max3_f32 v3, v3, v86, v87
	v_max3_f32 v3, v3, v88, v89
	v_max3_f32 v3, v3, v90, v91
	v_max3_f32 v3, v3, v92, v93
	v_max3_f32 v3, v3, v94, v95
	v_max3_f32 v3, v3, v96, v97
	s_waitcnt lgkmcnt(0)
	v_mfma_f32_32x32x16_bf16 v[68:83], v[40:43], v[104:107], v[68:83]
	ds_read_b128 v[36:39], v220 offset:64
	ds_read_b128 v[40:43], v220 offset:96
	v_max3_f32 v3, v3, v98, v99
	s_waitcnt lgkmcnt(1)
	v_mfma_f32_32x32x16_bf16 v[68:83], v[36:39], v[108:111], v[68:83]
	s_waitcnt lgkmcnt(0)
	v_mfma_f32_32x32x16_bf16 v[68:83], v[40:43], v[112:115], v[68:83]
	s_nop 11
	v_max3_f32 v3, v3, v68, v69
	v_max3_f32 v3, v3, v70, v71
	v_max3_f32 v3, v3, v72, v73
	v_max3_f32 v3, v3, v74, v75
	v_max3_f32 v3, v3, v76, v77
	v_max3_f32 v3, v3, v78, v79
	v_max3_f32 v3, v3, v80, v81
	v_max3_f32 v3, v3, v82, v83
	ds_bpermute_b32 v36, v179, v3
	s_waitcnt lgkmcnt(0)
	v_max_f32_e32 v36, v36, v36
	v_max_f32_e32 v3, v3, v36
	v_max3_f32 v132, v218, v3, s46
	v_sub_f32_e32 v3, v218, v132
	v_exp_f32_e32 v170, v3
	s_nop 2
	v_cmp_eq_f32_e32 vcc, 1.0, v170
	s_cmp_eq_u64 vcc, exec
	s_nop 4
	s_cbranch_scc1 .LBB0_1425
	v_pk_mul_f32 v[34:35], v[34:35], v[170:171] op_sel_hi:[1,0]
	v_pk_mul_f32 v[32:33], v[32:33], v[170:171] op_sel_hi:[1,0]
	v_pk_mul_f32 v[30:31], v[30:31], v[170:171] op_sel_hi:[1,0]
	v_pk_mul_f32 v[28:29], v[28:29], v[170:171] op_sel_hi:[1,0]
	v_pk_mul_f32 v[26:27], v[26:27], v[170:171] op_sel_hi:[1,0]
	v_pk_mul_f32 v[24:25], v[24:25], v[170:171] op_sel_hi:[1,0]
	v_pk_mul_f32 v[22:23], v[22:23], v[170:171] op_sel_hi:[1,0]
	v_pk_mul_f32 v[20:21], v[20:21], v[170:171] op_sel_hi:[1,0]
	v_pk_mul_f32 v[18:19], v[18:19], v[170:171] op_sel_hi:[1,0]
	v_pk_mul_f32 v[16:17], v[16:17], v[170:171] op_sel_hi:[1,0]
	v_pk_mul_f32 v[14:15], v[14:15], v[170:171] op_sel_hi:[1,0]
	v_pk_mul_f32 v[12:13], v[12:13], v[170:171] op_sel_hi:[1,0]
	v_pk_mul_f32 v[10:11], v[10:11], v[170:171] op_sel_hi:[1,0]
	v_pk_mul_f32 v[8:9], v[8:9], v[170:171] op_sel_hi:[1,0]
	v_pk_mul_f32 v[6:7], v[6:7], v[170:171] op_sel_hi:[1,0]
	v_pk_mul_f32 v[4:5], v[4:5], v[170:171] op_sel_hi:[1,0]
.LBB0_1425:
	v_add_u32_e32 v3, v219, v196
	v_pk_add_f32 v[84:85], v[84:85], v[132:133] op_sel_hi:[1,0] neg_lo:[0,1] neg_hi:[0,1]
	v_pk_add_f32 v[86:87], v[86:87], v[132:133] op_sel_hi:[1,0] neg_lo:[0,1] neg_hi:[0,1]
	v_pk_add_f32 v[88:89], v[88:89], v[132:133] op_sel_hi:[1,0] neg_lo:[0,1] neg_hi:[0,1]
	v_pk_add_f32 v[90:91], v[90:91], v[132:133] op_sel_hi:[1,0] neg_lo:[0,1] neg_hi:[0,1]
	v_add_u32_e32 v171, v3, v190
	v_exp_f32_e32 v84, v84
	v_exp_f32_e32 v85, v85
	v_exp_f32_e32 v86, v86
	v_exp_f32_e32 v87, v87
	v_exp_f32_e32 v88, v88
	v_exp_f32_e32 v89, v89
	v_exp_f32_e32 v90, v90
	v_exp_f32_e32 v91, v91
	v_add_u32_e32 v171, 0x2000, v171
	ds_read2_b64 v[224:227], v171 offset0:128 offset1:130
	ds_read2_b64 v[228:231], v171 offset0:132 offset1:134
	v_add_u32_e32 v3, v3, v191
	v_cvt_pk_bf16_f32 v220, v84, v85
	v_cvt_pk_bf16_f32 v221, v86, v87
	v_cvt_pk_bf16_f32 v222, v88, v89
	v_cvt_pk_bf16_f32 v223, v90, v91
	v_add_u32_e32 v3, 0x2000, v3
	v_pk_add_f32 v[92:93], v[92:93], v[132:133] op_sel_hi:[1,0] neg_lo:[0,1] neg_hi:[0,1]
	s_waitcnt lgkmcnt(1)
	v_mfma_f32_32x32x16_bf16 v[20:35], v[224:227], v[220:223], v[20:35]
	ds_read2_b64 v[224:227], v3 offset0:128 offset1:130
	ds_read2_b64 v[232:235], v3 offset0:132 offset1:134
	v_add_f32_e64 v94, v94, -v132
	v_add_f32_e64 v95, v95, -v132
	v_add_f32_e64 v96, v96, -v132
	v_add_f32_e64 v97, v97, -v132
	v_pk_add_f32 v[98:99], v[98:99], v[132:133] op_sel_hi:[1,0] neg_lo:[0,1] neg_hi:[0,1]
	v_exp_f32_e32 v92, v92
	v_exp_f32_e32 v93, v93
	v_exp_f32_e32 v94, v94
	s_waitcnt lgkmcnt(1)
	v_mfma_f32_32x32x16_bf16 v[4:19], v[224:227], v[220:223], v[4:19]
	v_exp_f32_e32 v95, v95
	v_exp_f32_e32 v96, v96
	v_exp_f32_e32 v97, v97
	v_exp_f32_e32 v98, v98
	v_exp_f32_e32 v99, v99
	v_cvt_pk_bf16_f32 v220, v92, v93
	v_cvt_pk_bf16_f32 v221, v94, v95
	v_cvt_pk_bf16_f32 v222, v96, v97
	v_cvt_pk_bf16_f32 v223, v98, v99
	s_nop 1
	v_mfma_f32_32x32x16_bf16 v[20:35], v[228:231], v[220:223], v[20:35]
	s_waitcnt lgkmcnt(0)
	v_mfma_f32_32x32x16_bf16 v[4:19], v[232:235], v[220:223], v[4:19]
	v_add_f32_e64 v74, v74, -v132
	v_add_f32_e64 v75, v75, -v132
	v_add_f32_e64 v68, v68, -v132
	v_add_f32_e64 v69, v69, -v132
	v_add_f32_e64 v70, v70, -v132
	v_add_f32_e64 v71, v71, -v132
	v_pk_add_f32 v[72:73], v[72:73], v[132:133] op_sel_hi:[1,0] neg_lo:[0,1] neg_hi:[0,1]
	v_exp_f32_e32 v228, v74
	v_exp_f32_e32 v229, v75
	v_pk_add_f32 v[74:75], v[76:77], v[132:133] op_sel_hi:[1,0] neg_lo:[0,1] neg_hi:[0,1]
	v_exp_f32_e32 v68, v68
	v_exp_f32_e32 v69, v69
	v_exp_f32_e32 v70, v70
	v_exp_f32_e32 v71, v71
	v_exp_f32_e32 v72, v72
	v_exp_f32_e32 v73, v73
	v_exp_f32_e32 v230, v74
	v_exp_f32_e32 v231, v75
	v_pk_add_f32 v[74:75], v[78:79], v[132:133] op_sel_hi:[1,0] neg_lo:[0,1] neg_hi:[0,1]
	v_cvt_pk_bf16_f32 v76, v72, v73
	v_exp_f32_e32 v232, v74
	v_exp_f32_e32 v233, v75
	v_pk_add_f32 v[74:75], v[80:81], v[132:133] op_sel_hi:[1,0] neg_lo:[0,1] neg_hi:[0,1]
	ds_read2_b64 v[78:81], v171 offset0:136 offset1:138
	ds_read2_b64 v[220:223], v171 offset0:140 offset1:142
	v_exp_f32_e32 v234, v74
	v_exp_f32_e32 v235, v75
	v_pk_add_f32 v[74:75], v[82:83], v[132:133] op_sel_hi:[1,0] neg_lo:[0,1] neg_hi:[0,1]
	v_cvt_pk_bf16_f32 v77, v228, v229
	v_exp_f32_e32 v82, v74
	v_exp_f32_e32 v83, v75
	v_cvt_pk_bf16_f32 v74, v68, v69
	v_cvt_pk_bf16_f32 v75, v70, v71
	s_mov_b64 s[26:27], 0
	s_waitcnt lgkmcnt(1)
	v_mfma_f32_32x32x16_bf16 v[20:35], v[78:81], v[74:77], v[20:35]
	ds_read2_b64 v[78:81], v3 offset0:136 offset1:138
	ds_read2_b64 v[224:227], v3 offset0:140 offset1:142
	s_waitcnt lgkmcnt(1)
	v_mfma_f32_32x32x16_bf16 v[4:19], v[78:81], v[74:77], v[4:19]
	v_cvt_pk_bf16_f32 v74, v230, v231
	v_cvt_pk_bf16_f32 v75, v232, v233
	v_cvt_pk_bf16_f32 v76, v234, v235
	v_cvt_pk_bf16_f32 v77, v82, v83
	s_nop 1
	v_mfma_f32_32x32x16_bf16 v[20:35], v[220:223], v[74:77], v[20:35]
	s_waitcnt lgkmcnt(0)
	v_mfma_f32_32x32x16_bf16 v[4:19], v[224:227], v[74:77], v[4:19]
	v_add_f32_e64 v74, v84, 0
	v_add_f32_e64 v75, v85, 0
	v_add_f32_e64 v74, v86, v74
	v_add_f32_e64 v75, v87, v75
	v_add_f32_e64 v74, v88, v74
	v_add_f32_e64 v75, v89, v75
	v_pk_add_f32 v[74:75], v[90:91], v[74:75]
	s_nop 0
	v_pk_add_f32 v[74:75], v[92:93], v[74:75]
	s_nop 0
	v_pk_add_f32 v[74:75], v[94:95], v[74:75]
	s_nop 0
	v_pk_add_f32 v[74:75], v[96:97], v[74:75]
	s_nop 0
	v_pk_add_f32 v[74:75], v[98:99], v[74:75]
	s_nop 0
	v_pk_add_f32 v[68:69], v[68:69], v[74:75]
	s_nop 0
	v_pk_add_f32 v[68:69], v[70:71], v[68:69]
	s_nop 0
	v_pk_add_f32 v[68:69], v[72:73], v[68:69]
	s_nop 0
	v_pk_add_f32 v[68:69], v[228:229], v[68:69]
	s_nop 0
	v_pk_add_f32 v[68:69], v[230:231], v[68:69]
	s_nop 0
	v_pk_add_f32 v[68:69], v[232:233], v[68:69]
	s_nop 0
	v_pk_add_f32 v[68:69], v[234:235], v[68:69]
	s_nop 0
	v_pk_add_f32 v[68:69], v[82:83], v[68:69]
	s_nop 0
	v_add_f32_e32 v3, v68, v69
	ds_bpermute_b32 v68, v179, v3
	s_waitcnt lgkmcnt(0)
	v_add_f32_e32 v3, v3, v68
	v_fmac_f32_e32 v3, v217, v170

.LBB0_1427:
	v_sub_u32_e32 v68, v161, v165
	s_cmp_gt_i32 s42, s76
	v_cvt_f32_i32_e32 v220, v68
	s_cselect_b64 s[2:3], -1, 0
	s_and_b64 s[8:9], s[24:25], s[2:3]
	v_add_u32_e32 v69, s38, v176
	s_mov_b64 s[2:3], -1
	s_andn2_b64 vcc, exec, s[8:9]
	v_add_u32_e32 v219, v69, v177
	v_add_u32_e32 v165, v69, v178
	s_cbranch_vccz .LBB0_1431
	v_mov_b32_e32 v3, v157
	ds_read_b128 v[52:55], v219
	ds_read_b128 v[56:59], v219 offset:32
	v_mul_f32_e64 v66, v220, -v3
	v_mov_b32_e32 v78, v3
	v_fma_f32 v38, 0, v3, v66
	v_fmamk_f32 v42, v3, 0x41000000, v66
	v_fmamk_f32 v46, v3, 0x41800000, v66
	v_fmamk_f32 v50, v3, 0x41c00000, v66
	v_pk_add_f32 v[36:37], v[2:3], v[38:39] op_sel_hi:[1,0]
	v_pk_fma_f32 v[38:39], v[78:79], s[64:65], v[38:39] op_sel_hi:[0,1,0]
	v_pk_add_f32 v[40:41], v[2:3], v[42:43] op_sel_hi:[1,0]
	v_pk_fma_f32 v[42:43], v[78:79], s[64:65], v[42:43] op_sel_hi:[0,1,0]
	v_pk_add_f32 v[44:45], v[2:3], v[46:47] op_sel_hi:[1,0]
	v_pk_fma_f32 v[46:47], v[78:79], s[64:65], v[46:47] op_sel_hi:[0,1,0]
	v_pk_add_f32 v[48:49], v[2:3], v[50:51] op_sel_hi:[1,0]
	v_pk_fma_f32 v[50:51], v[78:79], s[64:65], v[50:51] op_sel_hi:[0,1,0]
	v_fmamk_f32 v60, v3, 0x42200000, v66
	v_fmamk_f32 v62, v3, 0x42400000, v66
	s_waitcnt lgkmcnt(1)
	v_mfma_f32_32x32x16_bf16 v[36:51], v[52:55], v[100:103], v[36:51]
	v_cmp_gt_u32_e32 vcc, s47, v68
	s_waitcnt lgkmcnt(0)
	v_mfma_f32_32x32x16_bf16 v[36:51], v[56:59], v[104:107], v[36:51]
	ds_read_b128 v[52:55], v219 offset:64
	ds_read_b128 v[56:59], v219 offset:96
	ds_read_b128 v[70:73], v165
	ds_read_b128 v[74:77], v165 offset:32
	s_waitcnt lgkmcnt(3)
	v_mfma_f32_32x32x16_bf16 v[36:51], v[52:55], v[108:111], v[36:51]
	v_fmamk_f32 v54, v3, 0x42000000, v66
	v_fmac_f32_e32 v66, 0x42600000, v3
	v_add_f32_e64 v52, v2, v54
	v_add_f32_e64 v53, v3, v54
	v_pk_fma_f32 v[54:55], v[78:79], s[64:65], v[54:55] op_sel_hi:[0,1,0]
	v_pk_add_f32 v[64:65], v[2:3], v[66:67] op_sel_hi:[1,0]
	v_pk_fma_f32 v[66:67], v[78:79], s[64:65], v[66:67] op_sel_hi:[0,1,0]
	s_waitcnt lgkmcnt(2)
	v_mfma_f32_32x32x16_bf16 v[36:51], v[56:59], v[112:115], v[36:51]
	v_add_f32_e64 v56, v2, v60
	v_add_f32_e64 v57, v3, v60
	v_fma_f32 v58, v78, s64, v60
	v_fma_f32 v59, v78, s65, v60
	v_add_f32_e64 v60, v2, v62
	v_add_f32_e64 v61, v3, v62
	v_pk_fma_f32 v[62:63], v[78:79], s[64:65], v[62:63] op_sel_hi:[0,1,0]
	v_add_u32_e32 v3, -1, v68
	s_nop 3
	v_cndmask_b32_e32 v88, v214, v36, vcc
	s_waitcnt lgkmcnt(1)
	v_mfma_f32_32x32x16_bf16 v[52:67], v[70:73], v[100:103], v[52:67]
	ds_read_b128 v[70:73], v165 offset:64
	ds_read_b128 v[78:81], v165 offset:96
	v_cmp_gt_u32_e32 vcc, s47, v3
	v_add_u32_e32 v36, -2, v68
	s_nop 0
	v_cndmask_b32_e32 v89, v214, v37, vcc
	v_cmp_gt_u32_e32 vcc, s47, v36
	v_add_u32_e32 v36, -3, v68
	s_waitcnt lgkmcnt(2)
	v_mfma_f32_32x32x16_bf16 v[52:67], v[74:77], v[104:107], v[52:67]
	v_cndmask_b32_e32 v94, v214, v38, vcc
	v_cmp_gt_u32_e32 vcc, s47, v36
	v_add_u32_e32 v36, -8, v68
	v_max3_f32 v3, v88, s97, v89
	v_cndmask_b32_e32 v95, v214, v39, vcc
	v_cmp_gt_u32_e32 vcc, s47, v36
	v_add_u32_e32 v36, -9, v68
	s_waitcnt lgkmcnt(1)
	v_mfma_f32_32x32x16_bf16 v[52:67], v[70:73], v[108:111], v[52:67]
	v_cndmask_b32_e32 v96, v214, v40, vcc
	v_cmp_gt_u32_e32 vcc, s47, v36
	v_add_u32_e32 v36, -10, v68
	v_max3_f32 v3, v3, v94, v95
	v_cndmask_b32_e32 v97, v214, v41, vcc
	v_cmp_gt_u32_e32 vcc, s47, v36
	v_add_u32_e32 v36, -11, v68
	s_waitcnt lgkmcnt(0)
	v_mfma_f32_32x32x16_bf16 v[52:67], v[78:81], v[112:115], v[52:67]
	v_cndmask_b32_e32 v98, v214, v42, vcc
	v_cmp_gt_u32_e32 vcc, s47, v36
	v_add_u32_e32 v36, -16, v68
	v_max3_f32 v3, v3, v96, v97
	v_cndmask_b32_e32 v99, v214, v43, vcc
	v_cmp_gt_u32_e32 vcc, s47, v36
	v_subrev_u32_e32 v36, 17, v68
	v_max3_f32 v3, v3, v98, v99
	v_cndmask_b32_e32 v170, v214, v44, vcc
	v_cmp_gt_u32_e32 vcc, s47, v36
	v_subrev_u32_e32 v36, 18, v68
	s_nop 0
	v_cndmask_b32_e32 v171, v214, v45, vcc
	v_cmp_gt_u32_e32 vcc, s47, v36
	v_subrev_u32_e32 v36, 19, v68
	v_max3_f32 v3, v3, v170, v171
	v_cndmask_b32_e32 v90, v214, v46, vcc
	v_cmp_gt_u32_e32 vcc, s47, v36
	v_subrev_u32_e32 v36, 24, v68
	s_nop 0
	v_cndmask_b32_e32 v91, v214, v47, vcc
	v_cmp_gt_u32_e32 vcc, s47, v36
	v_subrev_u32_e32 v36, 25, v68
	v_max3_f32 v3, v3, v90, v91
	v_cndmask_b32_e32 v92, v214, v48, vcc
	v_cmp_gt_u32_e32 vcc, s47, v36
	v_subrev_u32_e32 v36, 26, v68
	s_nop 0
	v_cndmask_b32_e32 v93, v214, v49, vcc
	v_cmp_gt_u32_e32 vcc, s47, v36
	v_subrev_u32_e32 v36, 27, v68
	v_max3_f32 v3, v3, v92, v93
	v_cndmask_b32_e32 v86, v214, v50, vcc
	v_cmp_gt_u32_e32 vcc, s47, v36
	v_subrev_u32_e32 v36, 32, v68
	s_nop 0
	v_cndmask_b32_e32 v87, v214, v51, vcc
	v_cmp_gt_u32_e32 vcc, s47, v36
	v_subrev_u32_e32 v36, 33, v68
	v_max3_f32 v3, v3, v86, v87
	v_cndmask_b32_e32 v76, v214, v52, vcc
	v_cmp_gt_u32_e32 vcc, s47, v36
	v_subrev_u32_e32 v36, 34, v68
	s_nop 0
	v_cndmask_b32_e32 v77, v214, v53, vcc
	v_cmp_gt_u32_e32 vcc, s47, v36
	v_subrev_u32_e32 v36, 35, v68
	v_max3_f32 v3, v3, v76, v77
	v_cndmask_b32_e32 v78, v214, v54, vcc
	v_cmp_gt_u32_e32 vcc, s47, v36
	v_subrev_u32_e32 v36, 40, v68
	s_nop 0
	v_cndmask_b32_e32 v79, v214, v55, vcc
	v_cmp_gt_u32_e32 vcc, s47, v36
	v_subrev_u32_e32 v36, 41, v68
	v_max3_f32 v3, v3, v78, v79
	v_cndmask_b32_e32 v80, v214, v56, vcc
	v_cmp_gt_u32_e32 vcc, s47, v36
	v_subrev_u32_e32 v36, 42, v68
	s_nop 0
	v_cndmask_b32_e32 v81, v214, v57, vcc
	v_cmp_gt_u32_e32 vcc, s47, v36
	v_subrev_u32_e32 v36, 43, v68
	v_max3_f32 v3, v3, v80, v81
	v_cndmask_b32_e32 v82, v214, v58, vcc
	v_cmp_gt_u32_e32 vcc, s47, v36
	v_subrev_u32_e32 v36, 48, v68
	s_nop 0
	v_cndmask_b32_e32 v83, v214, v59, vcc
	v_cmp_gt_u32_e32 vcc, s47, v36
	v_subrev_u32_e32 v36, 49, v68
	v_max3_f32 v3, v3, v82, v83
	v_cndmask_b32_e32 v84, v214, v60, vcc
	v_cmp_gt_u32_e32 vcc, s47, v36
	v_subrev_u32_e32 v36, 50, v68
	s_nop 0
	v_cndmask_b32_e32 v85, v214, v61, vcc
	v_cmp_gt_u32_e32 vcc, s47, v36
	v_subrev_u32_e32 v36, 51, v68
	v_max3_f32 v3, v3, v84, v85
	v_cndmask_b32_e32 v74, v214, v62, vcc
	v_cmp_gt_u32_e32 vcc, s47, v36
	v_subrev_u32_e32 v36, 56, v68
	s_nop 0
	v_cndmask_b32_e32 v75, v214, v63, vcc
	v_cmp_gt_u32_e32 vcc, s47, v36
	v_subrev_u32_e32 v36, 57, v68
	v_max3_f32 v3, v3, v74, v75
	v_cndmask_b32_e32 v70, v214, v64, vcc
	v_cmp_gt_u32_e32 vcc, s47, v36
	v_subrev_u32_e32 v36, 58, v68
	s_nop 0
	v_cndmask_b32_e32 v71, v214, v65, vcc
	v_cmp_gt_u32_e32 vcc, s47, v36
	v_subrev_u32_e32 v36, 59, v68
	v_max3_f32 v3, v3, v70, v71
	v_cndmask_b32_e32 v72, v214, v66, vcc
	v_cmp_gt_u32_e32 vcc, s47, v36
	s_nop 1
	v_cndmask_b32_e32 v73, v214, v67, vcc
	v_max3_f32 v3, v3, v72, v73
	ds_bpermute_b32 v36, v179, v3
	s_nop 3
	s_waitcnt lgkmcnt(0)
	v_max_f32_e32 v36, v36, v36
	v_max_f32_e32 v3, v3, v36
	v_max3_f32 v132, v218, v3, s46
	v_sub_f32_e32 v3, v218, v132
	v_exp_f32_e32 v68, v3
	s_nop 2
	v_cmp_eq_f32_e32 vcc, 1.0, v68
	s_cmp_eq_u64 vcc, exec
	s_nop 8
	s_cbranch_scc1 .LBB0_1430
	v_pk_mul_f32 v[34:35], v[34:35], v[68:69] op_sel_hi:[1,0]
	v_pk_mul_f32 v[32:33], v[32:33], v[68:69] op_sel_hi:[1,0]
	v_pk_mul_f32 v[30:31], v[30:31], v[68:69] op_sel_hi:[1,0]
	v_pk_mul_f32 v[28:29], v[28:29], v[68:69] op_sel_hi:[1,0]
	v_pk_mul_f32 v[26:27], v[26:27], v[68:69] op_sel_hi:[1,0]
	v_pk_mul_f32 v[24:25], v[24:25], v[68:69] op_sel_hi:[1,0]
	v_pk_mul_f32 v[22:23], v[22:23], v[68:69] op_sel_hi:[1,0]
	v_pk_mul_f32 v[20:21], v[20:21], v[68:69] op_sel_hi:[1,0]
	v_pk_mul_f32 v[18:19], v[18:19], v[68:69] op_sel_hi:[1,0]
	v_pk_mul_f32 v[16:17], v[16:17], v[68:69] op_sel_hi:[1,0]
	v_pk_mul_f32 v[14:15], v[14:15], v[68:69] op_sel_hi:[1,0]
	v_pk_mul_f32 v[12:13], v[12:13], v[68:69] op_sel_hi:[1,0]
	v_pk_mul_f32 v[10:11], v[10:11], v[68:69] op_sel_hi:[1,0]
	v_pk_mul_f32 v[8:9], v[8:9], v[68:69] op_sel_hi:[1,0]
	v_pk_mul_f32 v[6:7], v[6:7], v[68:69] op_sel_hi:[1,0]
	v_pk_mul_f32 v[4:5], v[4:5], v[68:69] op_sel_hi:[1,0]
.LBB0_1430:
	v_pk_add_f32 v[94:95], v[94:95], v[132:133] op_sel_hi:[1,0] neg_lo:[0,1] neg_hi:[0,1]
	v_lshl_add_u32 v3, v136, 1, s38
	v_exp_f32_e32 v230, v94
	v_exp_f32_e32 v231, v95
	v_pk_add_f32 v[94:95], v[96:97], v[132:133] op_sel_hi:[1,0] neg_lo:[0,1] neg_hi:[0,1]
	v_pk_add_f32 v[88:89], v[88:89], v[132:133] op_sel_hi:[1,0] neg_lo:[0,1] neg_hi:[0,1]
	v_exp_f32_e32 v232, v94
	v_exp_f32_e32 v233, v95
	v_pk_add_f32 v[94:95], v[98:99], v[132:133] op_sel_hi:[1,0] neg_lo:[0,1] neg_hi:[0,1]
	v_exp_f32_e32 v88, v88
	v_exp_f32_e32 v98, v94
	v_add_u32_e32 v94, v3, v190
	v_add_u32_e32 v186, 0x2000, v94
	v_exp_f32_e32 v99, v95
	ds_read2_b64 v[94:97], v186 offset0:128 offset1:130
	v_add_u32_e32 v3, v3, v191
	v_add_u32_e32 v3, 0x2000, v3
	ds_read2_b64 v[226:229], v3 offset0:128 offset1:130
	v_exp_f32_e32 v89, v89
	v_pk_add_f32 v[90:91], v[90:91], v[132:133] op_sel_hi:[1,0] neg_lo:[0,1] neg_hi:[0,1]
	v_cvt_pk_bf16_f32 v223, v230, v231
	v_exp_f32_e32 v234, v90
	v_exp_f32_e32 v235, v91
	v_pk_add_f32 v[90:91], v[92:93], v[132:133] op_sel_hi:[1,0] neg_lo:[0,1] neg_hi:[0,1]
	v_cvt_pk_bf16_f32 v222, v88, v89
	v_cvt_pk_bf16_f32 v224, v232, v233
	v_cvt_pk_bf16_f32 v225, v98, v99
	v_exp_f32_e32 v236, v90
	v_exp_f32_e32 v237, v91
	ds_read2_b64 v[90:93], v186 offset0:132 offset1:134
	s_waitcnt lgkmcnt(2)
	v_mfma_f32_32x32x16_bf16 v[20:35], v[94:97], v[222:225], v[20:35]
	v_add_f32_e64 v170, v170, -v132
	v_add_f32_e64 v171, v171, -v132
	v_add_f32_e64 v86, v86, -v132
	v_add_f32_e64 v87, v87, -v132
	v_exp_f32_e32 v170, v170
	v_exp_f32_e32 v171, v171
	v_cvt_pk_bf16_f32 v95, v234, v235
	v_cvt_pk_bf16_f32 v96, v236, v237
	v_cvt_pk_bf16_f32 v94, v170, v171
	s_waitcnt lgkmcnt(1)
	v_mfma_f32_32x32x16_bf16 v[4:19], v[226:229], v[222:225], v[4:19]
	v_exp_f32_e32 v222, v86
	v_exp_f32_e32 v223, v87
	s_nop 0
	v_cvt_pk_bf16_f32 v97, v222, v223
	s_waitcnt lgkmcnt(0)
	s_nop 0
	v_mfma_f32_32x32x16_bf16 v[20:35], v[90:93], v[94:97], v[20:35]
	ds_read2_b64 v[90:93], v3 offset0:132 offset1:134
	s_waitcnt lgkmcnt(0)
	v_mfma_f32_32x32x16_bf16 v[4:19], v[90:93], v[94:97], v[4:19]
	v_add_f32_e64 v76, v76, -v132
	v_add_f32_e64 v77, v77, -v132
	v_add_f32_e64 v74, v74, -v132
	v_add_f32_e64 v75, v75, -v132
	v_exp_f32_e32 v90, v76
	v_exp_f32_e32 v91, v77
	v_pk_add_f32 v[76:77], v[78:79], v[132:133] op_sel_hi:[1,0] neg_lo:[0,1] neg_hi:[0,1]
	v_pk_add_f32 v[70:71], v[70:71], v[132:133] op_sel_hi:[1,0] neg_lo:[0,1] neg_hi:[0,1]
	v_exp_f32_e32 v92, v76
	v_exp_f32_e32 v93, v77
	v_pk_add_f32 v[76:77], v[80:81], v[132:133] op_sel_hi:[1,0] neg_lo:[0,1] neg_hi:[0,1]
	v_pk_add_f32 v[80:81], v[84:85], v[132:133] op_sel_hi:[1,0] neg_lo:[0,1] neg_hi:[0,1]
	v_exp_f32_e32 v94, v76
	v_exp_f32_e32 v95, v77
	v_pk_add_f32 v[76:77], v[82:83], v[132:133] op_sel_hi:[1,0] neg_lo:[0,1] neg_hi:[0,1]
	ds_read2_b64 v[84:87], v3 offset0:136 offset1:138
	v_exp_f32_e32 v96, v76
	v_exp_f32_e32 v97, v77
	ds_read2_b64 v[76:79], v186 offset0:136 offset1:138
	v_exp_f32_e32 v224, v80
	v_exp_f32_e32 v225, v81
	v_cvt_pk_bf16_f32 v80, v90, v91
	v_cvt_pk_bf16_f32 v81, v92, v93
	v_cvt_pk_bf16_f32 v82, v94, v95
	v_cvt_pk_bf16_f32 v83, v96, v97
	v_exp_f32_e32 v226, v74
	v_exp_f32_e32 v227, v75
	v_exp_f32_e32 v228, v70
	v_exp_f32_e32 v229, v71
	v_pk_add_f32 v[74:75], v[72:73], v[132:133] op_sel_hi:[1,0] neg_lo:[0,1] neg_hi:[0,1]
	ds_read2_b64 v[70:73], v186 offset0:140 offset1:142
	s_waitcnt lgkmcnt(1)
	v_mfma_f32_32x32x16_bf16 v[20:35], v[76:79], v[80:83], v[20:35]
	v_cvt_pk_bf16_f32 v78, v224, v225
	v_cvt_pk_bf16_f32 v79, v226, v227
	s_mov_b64 s[2:3], 0
	v_mfma_f32_32x32x16_bf16 v[4:19], v[84:87], v[80:83], v[4:19]
	v_exp_f32_e32 v82, v74
	v_exp_f32_e32 v83, v75
	v_cvt_pk_bf16_f32 v80, v228, v229
	ds_read2_b64 v[74:77], v3 offset0:140 offset1:142
	v_cvt_pk_bf16_f32 v81, v82, v83
	s_waitcnt lgkmcnt(1)
	s_nop 0
	v_mfma_f32_32x32x16_bf16 v[20:35], v[70:73], v[78:81], v[20:35]
	v_add_f32_e64 v70, v88, 0
	v_add_f32_e64 v71, v89, 0
	v_add_f32_e64 v70, v230, v70
	v_add_f32_e64 v71, v231, v71
	v_add_f32_e64 v70, v232, v70
	v_add_f32_e64 v71, v233, v71
	v_pk_add_f32 v[70:71], v[98:99], v[70:71]
	s_waitcnt lgkmcnt(0)
	v_mfma_f32_32x32x16_bf16 v[4:19], v[74:77], v[78:81], v[4:19]
	v_add_f32_e64 v70, v170, v70
	v_add_f32_e64 v71, v171, v71
	v_add_f32_e64 v70, v234, v70
	v_add_f32_e64 v71, v235, v71
	v_add_f32_e64 v70, v236, v70
	v_add_f32_e64 v71, v237, v71
	v_pk_add_f32 v[70:71], v[222:223], v[70:71]
	s_nop 0
	v_pk_add_f32 v[70:71], v[90:91], v[70:71]
	s_nop 0
	v_pk_add_f32 v[70:71], v[92:93], v[70:71]
	s_nop 0
	v_pk_add_f32 v[70:71], v[94:95], v[70:71]
	s_nop 0
	v_pk_add_f32 v[70:71], v[96:97], v[70:71]
	s_nop 0
	v_pk_add_f32 v[70:71], v[224:225], v[70:71]
	s_nop 0
	v_pk_add_f32 v[70:71], v[226:227], v[70:71]
	s_nop 0
	v_pk_add_f32 v[70:71], v[228:229], v[70:71]
	s_nop 0
	v_pk_add_f32 v[70:71], v[82:83], v[70:71]
	s_nop 0
	v_add_f32_e32 v3, v70, v71
	ds_bpermute_b32 v70, v179, v3
	s_waitcnt lgkmcnt(0)
	v_add_f32_e32 v3, v3, v70
	v_fmac_f32_e32 v3, v217, v68

.LBB0_1434:
	v_add_u32_e32 v3, v69, v196
	v_pk_add_f32 v[52:53], v[52:53], v[132:133] op_sel_hi:[1,0] neg_lo:[0,1] neg_hi:[0,1]
	v_pk_add_f32 v[54:55], v[54:55], v[132:133] op_sel_hi:[1,0] neg_lo:[0,1] neg_hi:[0,1]
	v_pk_add_f32 v[56:57], v[56:57], v[132:133] op_sel_hi:[1,0] neg_lo:[0,1] neg_hi:[0,1]
	v_pk_add_f32 v[58:59], v[58:59], v[132:133] op_sel_hi:[1,0] neg_lo:[0,1] neg_hi:[0,1]
	v_add_u32_e32 v69, v3, v190
	v_exp_f32_e32 v52, v52
	v_exp_f32_e32 v53, v53
	v_exp_f32_e32 v54, v54
	v_exp_f32_e32 v55, v55
	v_exp_f32_e32 v56, v56
	v_exp_f32_e32 v57, v57
	v_exp_f32_e32 v58, v58
	v_exp_f32_e32 v59, v59
	v_add_u32_e32 v69, 0x2000, v69
	ds_read2_b64 v[74:77], v69 offset0:128 offset1:130
	ds_read2_b64 v[78:81], v69 offset0:132 offset1:134
	v_add_u32_e32 v3, v3, v191
	v_cvt_pk_bf16_f32 v70, v52, v53
	v_cvt_pk_bf16_f32 v71, v54, v55
	v_cvt_pk_bf16_f32 v72, v56, v57
	v_cvt_pk_bf16_f32 v73, v58, v59
	v_add_u32_e32 v3, 0x2000, v3
	v_pk_add_f32 v[60:61], v[60:61], v[132:133] op_sel_hi:[1,0] neg_lo:[0,1] neg_hi:[0,1]
	s_waitcnt lgkmcnt(1)
	v_mfma_f32_32x32x16_bf16 v[20:35], v[74:77], v[70:73], v[20:35]
	ds_read2_b64 v[74:77], v3 offset0:128 offset1:130
	ds_read2_b64 v[82:85], v3 offset0:132 offset1:134
	v_add_f32_e64 v62, v62, -v132
	v_add_f32_e64 v63, v63, -v132
	v_add_f32_e64 v64, v64, -v132
	v_add_f32_e64 v65, v65, -v132
	v_pk_add_f32 v[66:67], v[66:67], v[132:133] op_sel_hi:[1,0] neg_lo:[0,1] neg_hi:[0,1]
	v_exp_f32_e32 v60, v60
	v_exp_f32_e32 v61, v61
	v_exp_f32_e32 v62, v62
	s_waitcnt lgkmcnt(1)
	v_mfma_f32_32x32x16_bf16 v[4:19], v[74:77], v[70:73], v[4:19]
	v_exp_f32_e32 v63, v63
	v_exp_f32_e32 v64, v64
	v_exp_f32_e32 v65, v65
	v_exp_f32_e32 v66, v66
	v_exp_f32_e32 v67, v67
	v_cvt_pk_bf16_f32 v70, v60, v61
	v_cvt_pk_bf16_f32 v71, v62, v63
	v_cvt_pk_bf16_f32 v72, v64, v65
	v_cvt_pk_bf16_f32 v73, v66, v67
	s_nop 1
	v_mfma_f32_32x32x16_bf16 v[20:35], v[78:81], v[70:73], v[20:35]
	s_waitcnt lgkmcnt(0)
	v_mfma_f32_32x32x16_bf16 v[4:19], v[82:85], v[70:73], v[4:19]
	v_add_f32_e64 v42, v42, -v132
	v_add_f32_e64 v43, v43, -v132
	v_add_f32_e64 v36, v36, -v132
	v_add_f32_e64 v37, v37, -v132
	v_add_f32_e64 v38, v38, -v132
	v_add_f32_e64 v39, v39, -v132
	v_pk_add_f32 v[40:41], v[40:41], v[132:133] op_sel_hi:[1,0] neg_lo:[0,1] neg_hi:[0,1]
	v_exp_f32_e32 v78, v42
	v_exp_f32_e32 v79, v43
	v_pk_add_f32 v[42:43], v[44:45], v[132:133] op_sel_hi:[1,0] neg_lo:[0,1] neg_hi:[0,1]
	v_exp_f32_e32 v36, v36
	v_exp_f32_e32 v37, v37
	v_exp_f32_e32 v38, v38
	v_exp_f32_e32 v39, v39
	v_exp_f32_e32 v40, v40
	v_exp_f32_e32 v41, v41
	v_exp_f32_e32 v80, v42
	v_exp_f32_e32 v81, v43
	v_pk_add_f32 v[42:43], v[46:47], v[132:133] op_sel_hi:[1,0] neg_lo:[0,1] neg_hi:[0,1]
	v_cvt_pk_bf16_f32 v44, v40, v41
	v_exp_f32_e32 v82, v42
	v_exp_f32_e32 v83, v43
	v_pk_add_f32 v[42:43], v[48:49], v[132:133] op_sel_hi:[1,0] neg_lo:[0,1] neg_hi:[0,1]
	ds_read2_b64 v[46:49], v69 offset0:136 offset1:138
	ds_read2_b64 v[70:73], v69 offset0:140 offset1:142
	v_exp_f32_e32 v84, v42
	v_exp_f32_e32 v85, v43
	v_pk_add_f32 v[42:43], v[50:51], v[132:133] op_sel_hi:[1,0] neg_lo:[0,1] neg_hi:[0,1]
	v_cvt_pk_bf16_f32 v45, v78, v79
	v_exp_f32_e32 v50, v42
	v_exp_f32_e32 v51, v43
	v_cvt_pk_bf16_f32 v42, v36, v37
	v_cvt_pk_bf16_f32 v43, v38, v39
	s_waitcnt lgkmcnt(1)
	s_nop 0
	v_mfma_f32_32x32x16_bf16 v[20:35], v[46:49], v[42:45], v[20:35]
	ds_read2_b64 v[46:49], v3 offset0:136 offset1:138
	ds_read2_b64 v[74:77], v3 offset0:140 offset1:142
	s_waitcnt lgkmcnt(1)
	v_mfma_f32_32x32x16_bf16 v[4:19], v[46:49], v[42:45], v[4:19]
	v_cvt_pk_bf16_f32 v42, v80, v81
	v_cvt_pk_bf16_f32 v43, v82, v83
	v_cvt_pk_bf16_f32 v44, v84, v85
	v_cvt_pk_bf16_f32 v45, v50, v51
	s_nop 1
	v_mfma_f32_32x32x16_bf16 v[20:35], v[70:73], v[42:45], v[20:35]
	s_waitcnt lgkmcnt(0)
	v_mfma_f32_32x32x16_bf16 v[4:19], v[74:77], v[42:45], v[4:19]
	v_add_f32_e64 v42, v52, 0
	v_add_f32_e64 v43, v53, 0
	v_add_f32_e64 v42, v54, v42
	v_add_f32_e64 v43, v55, v43
	v_add_f32_e64 v42, v56, v42
	v_add_f32_e64 v43, v57, v43
	v_pk_add_f32 v[42:43], v[58:59], v[42:43]
	s_nop 0
	v_pk_add_f32 v[42:43], v[60:61], v[42:43]
	s_nop 0
	v_pk_add_f32 v[42:43], v[62:63], v[42:43]
	s_nop 0
	v_pk_add_f32 v[42:43], v[64:65], v[42:43]
	s_nop 0
	v_pk_add_f32 v[42:43], v[66:67], v[42:43]
	s_nop 0
	v_pk_add_f32 v[36:37], v[36:37], v[42:43]
	s_nop 0
	v_pk_add_f32 v[36:37], v[38:39], v[36:37]
	s_nop 0
	v_pk_add_f32 v[36:37], v[40:41], v[36:37]
	s_nop 0
	v_pk_add_f32 v[36:37], v[78:79], v[36:37]
	s_nop 0
	v_pk_add_f32 v[36:37], v[80:81], v[36:37]
	s_nop 0
	v_pk_add_f32 v[36:37], v[82:83], v[36:37]
	s_nop 0
	v_pk_add_f32 v[36:37], v[84:85], v[36:37]
	s_nop 0
	v_pk_add_f32 v[36:37], v[50:51], v[36:37]
	s_nop 0
	v_add_f32_e32 v3, v36, v37
	ds_bpermute_b32 v36, v179, v3
	s_waitcnt lgkmcnt(0)
	v_add_f32_e32 v3, v3, v36
	s_nop 0
	v_fmac_f32_e32 v3, v217, v68
	s_nop 6
	s_branch .LBB0_1442

.LBB0_1442:
	s_nop 15
	v_mov_b32_e32 v217, v3
	v_mov_b32_e32 v218, v132
.LBB0_1443:
	s_and_b64 vcc, exec, s[0:1]
	s_cbranch_vccnz .LBB0_1465
	v_lshrrev_b32_e32 v3, s39, v159
	v_and_b32_e32 v3, 1, v3
	v_cmp_eq_u32_e64 s[0:1], 1, v3
	s_or_b64 s[2:3], s[28:29], s[0:1]
	v_cndmask_b32_e64 v3, 0, 1, s[2:3]
	v_cmp_ne_u32_e32 vcc, 0, v3
	s_cbranch_vccz .LBB0_1465
	s_cmp_lt_i32 s39, s48
	s_cselect_b64 s[2:3], -1, 0
	s_cmp_ge_i32 s39, s48
	v_add_u32_e32 v165, s38, v176
	s_cselect_b64 s[26:27], -1, 0
	s_mov_b64 s[24:25], -1
	s_and_b64 vcc, exec, s[20:21]
	v_lshl_or_b32 v221, s39, 6, v136
	v_add_u32_e32 v220, v165, v177
	v_add_u32_e32 v219, v165, v178
	s_cbranch_vccz .LBB0_1454
	v_sub_u32_e32 v68, v161, v221
	v_cvt_f32_i32_e32 v69, v68
	s_and_b64 vcc, exec, s[26:27]
	s_cbranch_vccz .LBB0_1450
	v_mov_b32_e32 v3, v157
	ds_read_b128 v[52:55], v220 offset:17920
	ds_read_b128 v[56:59], v220 offset:17952
	v_mul_f32_e64 v36, v69, -v3
	v_cndmask_b32_e64 v66, v214, v36, s[0:1]
	v_mov_b32_e32 v74, v3
	v_fma_f32 v38, 0, v3, v66
	v_fmamk_f32 v42, v3, 0x41000000, v66
	v_fmamk_f32 v46, v3, 0x41800000, v66
	v_fmamk_f32 v50, v3, 0x41c00000, v66
	v_pk_add_f32 v[36:37], v[2:3], v[38:39] op_sel_hi:[1,0]
	v_pk_fma_f32 v[38:39], v[74:75], s[64:65], v[38:39] op_sel_hi:[0,1,0]
	v_pk_add_f32 v[40:41], v[2:3], v[42:43] op_sel_hi:[1,0]
	v_pk_fma_f32 v[42:43], v[74:75], s[64:65], v[42:43] op_sel_hi:[0,1,0]
	v_pk_add_f32 v[44:45], v[2:3], v[46:47] op_sel_hi:[1,0]
	v_pk_fma_f32 v[46:47], v[74:75], s[64:65], v[46:47] op_sel_hi:[0,1,0]
	v_pk_add_f32 v[48:49], v[2:3], v[50:51] op_sel_hi:[1,0]
	v_pk_fma_f32 v[50:51], v[74:75], s[64:65], v[50:51] op_sel_hi:[0,1,0]
	v_fmamk_f32 v62, v3, 0x42200000, v66
	v_fmamk_f32 v64, v3, 0x42400000, v66
	s_waitcnt lgkmcnt(1)
	v_mfma_f32_32x32x16_bf16 v[36:51], v[52:55], v[100:103], v[36:51]
	v_cmp_lt_i32_e32 vcc, -1, v68
	s_waitcnt lgkmcnt(0)
	v_mfma_f32_32x32x16_bf16 v[36:51], v[56:59], v[104:107], v[36:51]
	ds_read_b128 v[52:55], v220 offset:17984
	ds_read_b128 v[58:61], v220 offset:18016
	ds_read_b128 v[70:73], v219 offset:17920
	v_add_f32_e64 v56, v2, v62
	v_add_f32_e64 v57, v3, v62
	s_waitcnt lgkmcnt(2)
	v_mfma_f32_32x32x16_bf16 v[36:51], v[52:55], v[108:111], v[36:51]
	v_fmamk_f32 v54, v3, 0x42000000, v66
	v_fmac_f32_e32 v66, 0x42600000, v3
	v_add_f32_e64 v52, v2, v54
	v_add_f32_e64 v53, v3, v54
	v_pk_fma_f32 v[54:55], v[74:75], s[64:65], v[54:55] op_sel_hi:[0,1,0]
	s_waitcnt lgkmcnt(1)
	v_mfma_f32_32x32x16_bf16 v[36:51], v[58:61], v[112:115], v[36:51]
	v_fma_f32 v58, v74, s64, v62
	v_fma_f32 v59, v74, s65, v62
	v_add_f32_e64 v60, v2, v64
	v_add_f32_e64 v61, v3, v64
	v_fma_f32 v62, v74, s64, v64
	v_fma_f32 v63, v74, s65, v64
	v_pk_add_f32 v[64:65], v[2:3], v[66:67] op_sel_hi:[1,0]
	v_pk_fma_f32 v[66:67], v[74:75], s[64:65], v[66:67] op_sel_hi:[0,1,0]
	ds_read_b128 v[74:77], v219 offset:17952
	s_nop 2
	v_cndmask_b32_e32 v86, v214, v36, vcc
	s_waitcnt lgkmcnt(1)
	v_mfma_f32_32x32x16_bf16 v[52:67], v[70:73], v[100:103], v[52:67]
	ds_read_b128 v[70:73], v219 offset:17984
	ds_read_b128 v[78:81], v219 offset:18016
	v_cmp_lt_i32_e32 vcc, 0, v68
	s_nop 1
	v_cndmask_b32_e32 v87, v214, v37, vcc
	v_cmp_lt_i32_e32 vcc, 1, v68
	v_max3_f32 v3, v86, s97, v87
	s_waitcnt lgkmcnt(2)
	v_mfma_f32_32x32x16_bf16 v[52:67], v[74:77], v[104:107], v[52:67]
	v_cndmask_b32_e32 v94, v214, v38, vcc
	v_cmp_lt_i32_e32 vcc, 2, v68
	s_nop 1
	v_cndmask_b32_e32 v95, v214, v39, vcc
	v_cmp_lt_i32_e32 vcc, 7, v68
	v_max3_f32 v3, v3, v94, v95
	s_waitcnt lgkmcnt(1)
	v_mfma_f32_32x32x16_bf16 v[52:67], v[70:73], v[108:111], v[52:67]
	v_cndmask_b32_e32 v98, v214, v40, vcc
	v_cmp_lt_i32_e32 vcc, 8, v68
	s_nop 1
	v_cndmask_b32_e32 v99, v214, v41, vcc
	v_cmp_lt_i32_e32 vcc, 9, v68
	v_max3_f32 v3, v3, v98, v99
	s_waitcnt lgkmcnt(0)
	v_mfma_f32_32x32x16_bf16 v[52:67], v[78:81], v[112:115], v[52:67]
	v_cndmask_b32_e32 v96, v214, v42, vcc
	v_cmp_lt_i32_e32 vcc, 10, v68
	s_nop 1
	v_cndmask_b32_e32 v97, v214, v43, vcc
	v_cmp_lt_i32_e32 vcc, 15, v68
	v_max3_f32 v3, v3, v96, v97
	s_nop 0
	v_cndmask_b32_e32 v170, v214, v44, vcc
	v_cmp_lt_i32_e32 vcc, 16, v68
	s_nop 1
	v_cndmask_b32_e32 v171, v214, v45, vcc
	v_cmp_lt_i32_e32 vcc, 17, v68
	v_max3_f32 v3, v3, v170, v171
	s_nop 0
	v_cndmask_b32_e32 v90, v214, v46, vcc
	v_cmp_lt_i32_e32 vcc, 18, v68
	s_nop 1
	v_cndmask_b32_e32 v91, v214, v47, vcc
	v_cmp_lt_i32_e32 vcc, 23, v68
	v_max3_f32 v3, v3, v90, v91
	s_nop 0
	v_cndmask_b32_e32 v92, v214, v48, vcc
	v_cmp_lt_i32_e32 vcc, 24, v68
	s_nop 1
	v_cndmask_b32_e32 v93, v214, v49, vcc
	v_cmp_lt_i32_e32 vcc, 25, v68
	v_max3_f32 v3, v3, v92, v93
	s_nop 0
	v_cndmask_b32_e32 v88, v214, v50, vcc
	v_cmp_lt_i32_e32 vcc, 26, v68
	s_nop 1
	v_cndmask_b32_e32 v89, v214, v51, vcc
	v_cmp_lt_i32_e32 vcc, 31, v68
	v_max3_f32 v3, v3, v88, v89
	s_nop 0
	v_cndmask_b32_e32 v84, v214, v52, vcc
	v_cmp_lt_i32_e32 vcc, 32, v68
	s_nop 1
	v_cndmask_b32_e32 v85, v214, v53, vcc
	v_cmp_lt_i32_e32 vcc, 33, v68
	v_max3_f32 v3, v3, v84, v85
	s_nop 0
	v_cndmask_b32_e32 v82, v214, v54, vcc
	v_cmp_lt_i32_e32 vcc, 34, v68
	s_nop 1
	v_cndmask_b32_e32 v83, v214, v55, vcc
	v_cmp_lt_i32_e32 vcc, 39, v68
	v_max3_f32 v3, v3, v82, v83
	s_nop 0
	v_cndmask_b32_e32 v80, v214, v56, vcc
	v_cmp_lt_i32_e32 vcc, 40, v68
	s_nop 1
	v_cndmask_b32_e32 v81, v214, v57, vcc
	v_cmp_lt_i32_e32 vcc, 41, v68
	v_max3_f32 v3, v3, v80, v81
	s_nop 0
	v_cndmask_b32_e32 v78, v214, v58, vcc
	v_cmp_lt_i32_e32 vcc, 42, v68
	s_nop 1
	v_cndmask_b32_e32 v79, v214, v59, vcc
	v_cmp_lt_i32_e32 vcc, 47, v68
	v_max3_f32 v3, v3, v78, v79
	s_nop 0
	v_cndmask_b32_e32 v76, v214, v60, vcc
	v_cmp_lt_i32_e32 vcc, 48, v68
	s_nop 1
	v_cndmask_b32_e32 v77, v214, v61, vcc
	v_cmp_lt_i32_e32 vcc, 49, v68
	v_max3_f32 v3, v3, v76, v77
	s_nop 0
	v_cndmask_b32_e32 v74, v214, v62, vcc
	v_cmp_lt_i32_e32 vcc, 50, v68
	s_nop 1
	v_cndmask_b32_e32 v75, v214, v63, vcc
	v_cmp_lt_i32_e32 vcc, 55, v68
	v_max3_f32 v3, v3, v74, v75
	s_nop 0
	v_cndmask_b32_e32 v70, v214, v64, vcc
	v_cmp_lt_i32_e32 vcc, 56, v68
	s_nop 1
	v_cndmask_b32_e32 v71, v214, v65, vcc
	v_cmp_lt_i32_e32 vcc, 57, v68
	v_max3_f32 v3, v3, v70, v71
	s_nop 0
	v_cndmask_b32_e32 v72, v214, v66, vcc
	v_cmp_lt_i32_e32 vcc, 58, v68
	s_nop 1
	v_cndmask_b32_e32 v73, v214, v67, vcc
	v_max3_f32 v3, v3, v72, v73
	ds_bpermute_b32 v36, v179, v3
	s_nop 3
	s_waitcnt lgkmcnt(0)
	v_max_f32_e32 v36, v36, v36
	v_max_f32_e32 v3, v3, v36
	v_max3_f32 v132, v218, v3, s46
	v_sub_f32_e32 v3, v218, v132
	v_exp_f32_e32 v68, v3
	s_nop 2
	v_cmp_eq_f32_e32 vcc, 1.0, v68
	s_cmp_eq_u64 vcc, exec
	s_nop 8
	s_cbranch_scc1 .LBB0_1449
	v_pk_mul_f32 v[34:35], v[34:35], v[68:69] op_sel_hi:[1,0]
	v_pk_mul_f32 v[32:33], v[32:33], v[68:69] op_sel_hi:[1,0]
	v_pk_mul_f32 v[30:31], v[30:31], v[68:69] op_sel_hi:[1,0]
	v_pk_mul_f32 v[28:29], v[28:29], v[68:69] op_sel_hi:[1,0]
	v_pk_mul_f32 v[26:27], v[26:27], v[68:69] op_sel_hi:[1,0]
	v_pk_mul_f32 v[24:25], v[24:25], v[68:69] op_sel_hi:[1,0]
	v_pk_mul_f32 v[22:23], v[22:23], v[68:69] op_sel_hi:[1,0]
	v_pk_mul_f32 v[20:21], v[20:21], v[68:69] op_sel_hi:[1,0]
	v_pk_mul_f32 v[18:19], v[18:19], v[68:69] op_sel_hi:[1,0]
	v_pk_mul_f32 v[16:17], v[16:17], v[68:69] op_sel_hi:[1,0]
	v_pk_mul_f32 v[14:15], v[14:15], v[68:69] op_sel_hi:[1,0]
	v_pk_mul_f32 v[12:13], v[12:13], v[68:69] op_sel_hi:[1,0]
	v_pk_mul_f32 v[10:11], v[10:11], v[68:69] op_sel_hi:[1,0]
	v_pk_mul_f32 v[8:9], v[8:9], v[68:69] op_sel_hi:[1,0]
	v_pk_mul_f32 v[6:7], v[6:7], v[68:69] op_sel_hi:[1,0]
	v_pk_mul_f32 v[4:5], v[4:5], v[68:69] op_sel_hi:[1,0]
.LBB0_1449:
	v_pk_add_f32 v[94:95], v[94:95], v[132:133] op_sel_hi:[1,0] neg_lo:[0,1] neg_hi:[0,1]
	v_lshl_add_u32 v3, v136, 1, s38
	v_exp_f32_e32 v230, v94
	v_exp_f32_e32 v231, v95
	v_pk_add_f32 v[94:95], v[98:99], v[132:133] op_sel_hi:[1,0] neg_lo:[0,1] neg_hi:[0,1]
	v_pk_add_f32 v[86:87], v[86:87], v[132:133] op_sel_hi:[1,0] neg_lo:[0,1] neg_hi:[0,1]
	v_exp_f32_e32 v98, v94
	v_exp_f32_e32 v99, v95
	v_pk_add_f32 v[94:95], v[96:97], v[132:133] op_sel_hi:[1,0] neg_lo:[0,1] neg_hi:[0,1]
	v_exp_f32_e32 v86, v86
	v_exp_f32_e32 v232, v94
	v_add_u32_e32 v94, v3, v190
	v_add_u32_e32 v186, 0x6800, v94
	v_exp_f32_e32 v233, v95
	ds_read2_b64 v[94:97], v186 offset0:64 offset1:66
	v_add_u32_e32 v3, v3, v191
	v_add_u32_e32 v3, 0x6800, v3
	ds_read2_b64 v[226:229], v3 offset0:64 offset1:66
	v_exp_f32_e32 v87, v87
	v_pk_add_f32 v[90:91], v[90:91], v[132:133] op_sel_hi:[1,0] neg_lo:[0,1] neg_hi:[0,1]
	v_cvt_pk_bf16_f32 v223, v230, v231
	v_exp_f32_e32 v234, v90
	v_exp_f32_e32 v235, v91
	v_pk_add_f32 v[90:91], v[92:93], v[132:133] op_sel_hi:[1,0] neg_lo:[0,1] neg_hi:[0,1]
	v_cvt_pk_bf16_f32 v222, v86, v87
	v_cvt_pk_bf16_f32 v224, v98, v99
	v_cvt_pk_bf16_f32 v225, v232, v233
	v_exp_f32_e32 v236, v90
	v_exp_f32_e32 v237, v91
	ds_read2_b64 v[90:93], v186 offset0:68 offset1:70
	s_waitcnt lgkmcnt(2)
	v_mfma_f32_32x32x16_bf16 v[20:35], v[94:97], v[222:225], v[20:35]
	v_add_f32_e64 v170, v170, -v132
	v_add_f32_e64 v171, v171, -v132
	v_add_f32_e64 v88, v88, -v132
	v_add_f32_e64 v89, v89, -v132
	v_exp_f32_e32 v170, v170
	v_exp_f32_e32 v171, v171
	v_cvt_pk_bf16_f32 v95, v234, v235
	v_cvt_pk_bf16_f32 v96, v236, v237
	v_cvt_pk_bf16_f32 v94, v170, v171
	s_waitcnt lgkmcnt(1)
	v_mfma_f32_32x32x16_bf16 v[4:19], v[226:229], v[222:225], v[4:19]
	v_exp_f32_e32 v222, v88
	v_exp_f32_e32 v223, v89
	s_nop 0
	v_cvt_pk_bf16_f32 v97, v222, v223
	s_waitcnt lgkmcnt(0)
	s_nop 0
	v_mfma_f32_32x32x16_bf16 v[20:35], v[90:93], v[94:97], v[20:35]
	ds_read2_b64 v[88:91], v3 offset0:68 offset1:70
	s_waitcnt lgkmcnt(0)
	v_mfma_f32_32x32x16_bf16 v[4:19], v[88:91], v[94:97], v[4:19]
	v_add_f32_e64 v80, v80, -v132
	v_add_f32_e64 v81, v81, -v132
	v_add_f32_e64 v78, v78, -v132
	v_add_f32_e64 v79, v79, -v132
	v_exp_f32_e32 v94, v80
	v_exp_f32_e32 v95, v81
	v_exp_f32_e32 v96, v78
	v_exp_f32_e32 v97, v79
	v_pk_add_f32 v[80:81], v[76:77], v[132:133] op_sel_hi:[1,0] neg_lo:[0,1] neg_hi:[0,1]
	ds_read2_b64 v[76:79], v186 offset0:72 offset1:74
	v_pk_add_f32 v[84:85], v[84:85], v[132:133] op_sel_hi:[1,0] neg_lo:[0,1] neg_hi:[0,1]
	v_pk_add_f32 v[82:83], v[82:83], v[132:133] op_sel_hi:[1,0] neg_lo:[0,1] neg_hi:[0,1]
	ds_read2_b64 v[88:91], v3 offset0:72 offset1:74
	v_exp_f32_e32 v84, v84
	v_exp_f32_e32 v85, v85
	v_exp_f32_e32 v92, v82
	v_exp_f32_e32 v93, v83
	v_pk_add_f32 v[74:75], v[74:75], v[132:133] op_sel_hi:[1,0] neg_lo:[0,1] neg_hi:[0,1]
	v_pk_add_f32 v[70:71], v[70:71], v[132:133] op_sel_hi:[1,0] neg_lo:[0,1] neg_hi:[0,1]
	v_exp_f32_e32 v224, v80
	v_exp_f32_e32 v225, v81
	v_cvt_pk_bf16_f32 v80, v84, v85
	v_cvt_pk_bf16_f32 v81, v92, v93
	v_cvt_pk_bf16_f32 v82, v94, v95
	v_cvt_pk_bf16_f32 v83, v96, v97
	v_exp_f32_e32 v226, v74
	v_exp_f32_e32 v227, v75
	v_exp_f32_e32 v228, v70
	v_exp_f32_e32 v229, v71
	v_pk_add_f32 v[74:75], v[72:73], v[132:133] op_sel_hi:[1,0] neg_lo:[0,1] neg_hi:[0,1]
	ds_read2_b64 v[70:73], v186 offset0:76 offset1:78
	s_waitcnt lgkmcnt(2)
	v_mfma_f32_32x32x16_bf16 v[20:35], v[76:79], v[80:83], v[20:35]
	v_cvt_pk_bf16_f32 v78, v224, v225
	v_cvt_pk_bf16_f32 v79, v226, v227
	s_mov_b64 s[24:25], 0
	s_waitcnt lgkmcnt(1)
	v_mfma_f32_32x32x16_bf16 v[4:19], v[88:91], v[80:83], v[4:19]
	v_exp_f32_e32 v82, v74
	v_exp_f32_e32 v83, v75
	v_cvt_pk_bf16_f32 v80, v228, v229
	ds_read2_b64 v[74:77], v3 offset0:76 offset1:78
	v_cvt_pk_bf16_f32 v81, v82, v83
	s_waitcnt lgkmcnt(1)
	s_nop 0
	v_mfma_f32_32x32x16_bf16 v[20:35], v[70:73], v[78:81], v[20:35]
	v_add_f32_e64 v70, v86, 0
	v_add_f32_e64 v71, v87, 0
	v_add_f32_e64 v70, v230, v70
	v_add_f32_e64 v71, v231, v71
	v_add_f32_e64 v70, v98, v70
	v_add_f32_e64 v71, v99, v71
	v_pk_add_f32 v[70:71], v[232:233], v[70:71]
	s_waitcnt lgkmcnt(0)
	v_mfma_f32_32x32x16_bf16 v[4:19], v[74:77], v[78:81], v[4:19]
	v_add_f32_e64 v70, v170, v70
	v_add_f32_e64 v71, v171, v71
	v_add_f32_e64 v70, v234, v70
	v_add_f32_e64 v71, v235, v71
	v_add_f32_e64 v70, v236, v70
	v_add_f32_e64 v71, v237, v71
	v_pk_add_f32 v[70:71], v[222:223], v[70:71]
	s_nop 0
	v_pk_add_f32 v[70:71], v[84:85], v[70:71]
	s_nop 0
	v_pk_add_f32 v[70:71], v[92:93], v[70:71]
	s_nop 0
	v_pk_add_f32 v[70:71], v[94:95], v[70:71]
	s_nop 0
	v_pk_add_f32 v[70:71], v[96:97], v[70:71]
	s_nop 0
	v_pk_add_f32 v[70:71], v[224:225], v[70:71]
	s_nop 0
	v_pk_add_f32 v[70:71], v[226:227], v[70:71]
	s_nop 0
	v_pk_add_f32 v[70:71], v[228:229], v[70:71]
	s_nop 0
	v_pk_add_f32 v[70:71], v[82:83], v[70:71]
	s_nop 0
	v_add_f32_e32 v3, v70, v71
	ds_bpermute_b32 v70, v179, v3
	s_waitcnt lgkmcnt(0)
	v_add_f32_e32 v3, v3, v70
	v_fmac_f32_e32 v3, v217, v68
.LBB0_1450:
	s_and_b64 vcc, exec, s[24:25]
	s_cbranch_vccz .LBB0_1463
	v_mov_b32_e32 v3, v157
	s_nop 0
	v_mul_f32_e64 v36, v69, -v3
	v_cndmask_b32_e64 v44, v214, v36, s[0:1]
	v_mov_b32_e32 v46, v3
	v_fma_f32 v36, 0, v3, v44
	v_pk_add_f32 v[84:85], v[2:3], v[36:37] op_sel_hi:[1,0]
	v_pk_fma_f32 v[86:87], v[46:47], s[64:65], v[36:37] op_sel_hi:[0,1,0]
	ds_read_b128 v[36:39], v220 offset:17920
	v_fmamk_f32 v40, v3, 0x41000000, v44
	v_pk_add_f32 v[88:89], v[2:3], v[40:41] op_sel_hi:[1,0]
	v_pk_fma_f32 v[90:91], v[46:47], s[64:65], v[40:41] op_sel_hi:[0,1,0]
	v_fmamk_f32 v40, v3, 0x41800000, v44
	v_pk_add_f32 v[92:93], v[2:3], v[40:41] op_sel_hi:[1,0]
	v_pk_fma_f32 v[94:95], v[46:47], s[64:65], v[40:41] op_sel_hi:[0,1,0]
	v_fmamk_f32 v40, v3, 0x41c00000, v44
	v_pk_add_f32 v[96:97], v[2:3], v[40:41] op_sel_hi:[1,0]
	v_pk_fma_f32 v[98:99], v[46:47], s[64:65], v[40:41] op_sel_hi:[0,1,0]
	ds_read_b128 v[40:43], v220 offset:17952
	v_fmamk_f32 v48, v3, 0x42000000, v44
	s_waitcnt lgkmcnt(1)
	v_mfma_f32_32x32x16_bf16 v[84:99], v[36:39], v[100:103], v[84:99]
	v_fmamk_f32 v50, v3, 0x42200000, v44
	v_fmamk_f32 v52, v3, 0x42400000, v44
	v_fmac_f32_e32 v44, 0x42600000, v3
	v_add_f32_e64 v68, v2, v48
	v_add_f32_e64 v69, v3, v48
	v_pk_fma_f32 v[70:71], v[46:47], s[64:65], v[48:49] op_sel_hi:[0,1,0]
	v_pk_add_f32 v[72:73], v[2:3], v[50:51] op_sel_hi:[1,0]
	v_pk_fma_f32 v[74:75], v[46:47], s[64:65], v[50:51] op_sel_hi:[0,1,0]
	s_waitcnt lgkmcnt(0)
	v_mfma_f32_32x32x16_bf16 v[84:99], v[40:43], v[104:107], v[84:99]
	ds_read_b128 v[36:39], v220 offset:17984
	ds_read_b128 v[40:43], v220 offset:18016
	v_add_f32_e64 v76, v2, v52
	v_add_f32_e64 v77, v3, v52
	v_fma_f32 v78, v46, s64, v52
	v_fma_f32 v79, v46, s65, v52
	v_pk_add_f32 v[80:81], v[2:3], v[44:45] op_sel_hi:[1,0]
	v_pk_fma_f32 v[82:83], v[46:47], s[64:65], v[44:45] op_sel_hi:[0,1,0]
	s_nop 1
	s_waitcnt lgkmcnt(1)
	v_mfma_f32_32x32x16_bf16 v[84:99], v[36:39], v[108:111], v[84:99]
	ds_read_b128 v[36:39], v219 offset:17920
	s_nop 5
	s_waitcnt lgkmcnt(1)
	v_mfma_f32_32x32x16_bf16 v[84:99], v[40:43], v[112:115], v[84:99]
	ds_read_b128 v[40:43], v219 offset:17952
	s_waitcnt lgkmcnt(1)
	v_mfma_f32_32x32x16_bf16 v[68:83], v[36:39], v[100:103], v[68:83]
	s_nop 8
	v_max3_f32 v3, v84, s97, v85
	v_max3_f32 v3, v3, v86, v87
	v_max3_f32 v3, v3, v88, v89
	v_max3_f32 v3, v3, v90, v91
	v_max3_f32 v3, v3, v92, v93
	v_max3_f32 v3, v3, v94, v95
	v_max3_f32 v3, v3, v96, v97
	s_waitcnt lgkmcnt(0)
	v_mfma_f32_32x32x16_bf16 v[68:83], v[40:43], v[104:107], v[68:83]
	ds_read_b128 v[36:39], v219 offset:17984
	ds_read_b128 v[40:43], v219 offset:18016
	v_max3_f32 v3, v3, v98, v99
	s_waitcnt lgkmcnt(1)
	v_mfma_f32_32x32x16_bf16 v[68:83], v[36:39], v[108:111], v[68:83]
	s_waitcnt lgkmcnt(0)
	v_mfma_f32_32x32x16_bf16 v[68:83], v[40:43], v[112:115], v[68:83]
	s_nop 11
	v_max3_f32 v3, v3, v68, v69
	v_max3_f32 v3, v3, v70, v71
	v_max3_f32 v3, v3, v72, v73
	v_max3_f32 v3, v3, v74, v75
	v_max3_f32 v3, v3, v76, v77
	v_max3_f32 v3, v3, v78, v79
	v_max3_f32 v3, v3, v80, v81
	v_max3_f32 v3, v3, v82, v83
	ds_bpermute_b32 v36, v179, v3
	s_waitcnt lgkmcnt(0)
	v_max_f32_e32 v36, v36, v36
	v_max_f32_e32 v3, v3, v36
	v_max3_f32 v132, v218, v3, s46
	v_sub_f32_e32 v3, v218, v132
	v_exp_f32_e32 v170, v3
	s_nop 2
	v_cmp_eq_f32_e32 vcc, 1.0, v170
	s_cmp_eq_u64 vcc, exec
	s_nop 4
	s_cbranch_scc1 .LBB0_1453
	v_pk_mul_f32 v[34:35], v[34:35], v[170:171] op_sel_hi:[1,0]
	v_pk_mul_f32 v[32:33], v[32:33], v[170:171] op_sel_hi:[1,0]
	v_pk_mul_f32 v[30:31], v[30:31], v[170:171] op_sel_hi:[1,0]
	v_pk_mul_f32 v[28:29], v[28:29], v[170:171] op_sel_hi:[1,0]
	v_pk_mul_f32 v[26:27], v[26:27], v[170:171] op_sel_hi:[1,0]
	v_pk_mul_f32 v[24:25], v[24:25], v[170:171] op_sel_hi:[1,0]
	v_pk_mul_f32 v[22:23], v[22:23], v[170:171] op_sel_hi:[1,0]
	v_pk_mul_f32 v[20:21], v[20:21], v[170:171] op_sel_hi:[1,0]
	v_pk_mul_f32 v[18:19], v[18:19], v[170:171] op_sel_hi:[1,0]
	v_pk_mul_f32 v[16:17], v[16:17], v[170:171] op_sel_hi:[1,0]
	v_pk_mul_f32 v[14:15], v[14:15], v[170:171] op_sel_hi:[1,0]
	v_pk_mul_f32 v[12:13], v[12:13], v[170:171] op_sel_hi:[1,0]
	v_pk_mul_f32 v[10:11], v[10:11], v[170:171] op_sel_hi:[1,0]
	v_pk_mul_f32 v[8:9], v[8:9], v[170:171] op_sel_hi:[1,0]
	v_pk_mul_f32 v[6:7], v[6:7], v[170:171] op_sel_hi:[1,0]
	v_pk_mul_f32 v[4:5], v[4:5], v[170:171] op_sel_hi:[1,0]
.LBB0_1453:
	v_add_u32_e32 v3, v165, v196
	v_pk_add_f32 v[84:85], v[84:85], v[132:133] op_sel_hi:[1,0] neg_lo:[0,1] neg_hi:[0,1]
	v_pk_add_f32 v[86:87], v[86:87], v[132:133] op_sel_hi:[1,0] neg_lo:[0,1] neg_hi:[0,1]
	v_pk_add_f32 v[88:89], v[88:89], v[132:133] op_sel_hi:[1,0] neg_lo:[0,1] neg_hi:[0,1]
	v_pk_add_f32 v[90:91], v[90:91], v[132:133] op_sel_hi:[1,0] neg_lo:[0,1] neg_hi:[0,1]
	v_add_u32_e32 v171, v3, v190
	v_exp_f32_e32 v84, v84
	v_exp_f32_e32 v85, v85
	v_exp_f32_e32 v86, v86
	v_exp_f32_e32 v87, v87
	v_exp_f32_e32 v88, v88
	v_exp_f32_e32 v89, v89
	v_exp_f32_e32 v90, v90
	v_exp_f32_e32 v91, v91
	v_add_u32_e32 v171, 0x6800, v171
	ds_read2_b64 v[226:229], v171 offset0:64 offset1:66
	ds_read2_b64 v[230:233], v171 offset0:68 offset1:70
	v_add_u32_e32 v3, v3, v191
	v_cvt_pk_bf16_f32 v222, v84, v85
	v_cvt_pk_bf16_f32 v223, v86, v87
	v_cvt_pk_bf16_f32 v224, v88, v89
	v_cvt_pk_bf16_f32 v225, v90, v91
	v_add_u32_e32 v3, 0x6800, v3
	v_pk_add_f32 v[92:93], v[92:93], v[132:133] op_sel_hi:[1,0] neg_lo:[0,1] neg_hi:[0,1]
	s_waitcnt lgkmcnt(1)
	v_mfma_f32_32x32x16_bf16 v[20:35], v[226:229], v[222:225], v[20:35]
	ds_read2_b64 v[226:229], v3 offset0:64 offset1:66
	ds_read2_b64 v[234:237], v3 offset0:68 offset1:70
	v_add_f32_e64 v94, v94, -v132
	v_add_f32_e64 v95, v95, -v132
	v_add_f32_e64 v96, v96, -v132
	v_add_f32_e64 v97, v97, -v132
	v_pk_add_f32 v[98:99], v[98:99], v[132:133] op_sel_hi:[1,0] neg_lo:[0,1] neg_hi:[0,1]
	v_exp_f32_e32 v92, v92
	v_exp_f32_e32 v93, v93
	v_exp_f32_e32 v94, v94
	s_waitcnt lgkmcnt(1)
	v_mfma_f32_32x32x16_bf16 v[4:19], v[226:229], v[222:225], v[4:19]
	v_exp_f32_e32 v95, v95
	v_exp_f32_e32 v96, v96
	v_exp_f32_e32 v97, v97
	v_exp_f32_e32 v98, v98
	v_exp_f32_e32 v99, v99
	v_cvt_pk_bf16_f32 v222, v92, v93
	v_cvt_pk_bf16_f32 v223, v94, v95
	v_cvt_pk_bf16_f32 v224, v96, v97
	v_cvt_pk_bf16_f32 v225, v98, v99
	s_nop 1
	v_mfma_f32_32x32x16_bf16 v[20:35], v[230:233], v[222:225], v[20:35]
	s_waitcnt lgkmcnt(0)
	v_mfma_f32_32x32x16_bf16 v[4:19], v[234:237], v[222:225], v[4:19]
	v_add_f32_e64 v74, v74, -v132
	v_add_f32_e64 v75, v75, -v132
	v_add_f32_e64 v68, v68, -v132
	v_add_f32_e64 v69, v69, -v132
	v_add_f32_e64 v70, v70, -v132
	v_add_f32_e64 v71, v71, -v132
	v_pk_add_f32 v[72:73], v[72:73], v[132:133] op_sel_hi:[1,0] neg_lo:[0,1] neg_hi:[0,1]
	v_exp_f32_e32 v230, v74
	v_exp_f32_e32 v231, v75
	v_pk_add_f32 v[74:75], v[76:77], v[132:133] op_sel_hi:[1,0] neg_lo:[0,1] neg_hi:[0,1]
	v_exp_f32_e32 v68, v68
	v_exp_f32_e32 v69, v69
	v_exp_f32_e32 v70, v70
	v_exp_f32_e32 v71, v71
	v_exp_f32_e32 v72, v72
	v_exp_f32_e32 v73, v73
	v_exp_f32_e32 v232, v74
	v_exp_f32_e32 v233, v75
	v_pk_add_f32 v[74:75], v[78:79], v[132:133] op_sel_hi:[1,0] neg_lo:[0,1] neg_hi:[0,1]
	v_cvt_pk_bf16_f32 v76, v72, v73
	v_exp_f32_e32 v234, v74
	v_exp_f32_e32 v235, v75
	v_pk_add_f32 v[74:75], v[80:81], v[132:133] op_sel_hi:[1,0] neg_lo:[0,1] neg_hi:[0,1]
	ds_read2_b64 v[78:81], v171 offset0:72 offset1:74
	ds_read2_b64 v[222:225], v171 offset0:76 offset1:78
	v_exp_f32_e32 v236, v74
	v_exp_f32_e32 v237, v75
	v_pk_add_f32 v[74:75], v[82:83], v[132:133] op_sel_hi:[1,0] neg_lo:[0,1] neg_hi:[0,1]
	v_cvt_pk_bf16_f32 v77, v230, v231
	v_exp_f32_e32 v82, v74
	v_exp_f32_e32 v83, v75
	v_cvt_pk_bf16_f32 v74, v68, v69
	v_cvt_pk_bf16_f32 v75, v70, v71
	s_mov_b64 s[24:25], 0
	s_waitcnt lgkmcnt(1)
	v_mfma_f32_32x32x16_bf16 v[20:35], v[78:81], v[74:77], v[20:35]
	ds_read2_b64 v[78:81], v3 offset0:72 offset1:74
	ds_read2_b64 v[226:229], v3 offset0:76 offset1:78
	s_waitcnt lgkmcnt(1)
	v_mfma_f32_32x32x16_bf16 v[4:19], v[78:81], v[74:77], v[4:19]
	v_cvt_pk_bf16_f32 v74, v232, v233
	v_cvt_pk_bf16_f32 v75, v234, v235
	v_cvt_pk_bf16_f32 v76, v236, v237
	v_cvt_pk_bf16_f32 v77, v82, v83
	s_nop 1
	v_mfma_f32_32x32x16_bf16 v[20:35], v[222:225], v[74:77], v[20:35]
	s_waitcnt lgkmcnt(0)
	v_mfma_f32_32x32x16_bf16 v[4:19], v[226:229], v[74:77], v[4:19]
	v_add_f32_e64 v74, v84, 0
	v_add_f32_e64 v75, v85, 0
	v_add_f32_e64 v74, v86, v74
	v_add_f32_e64 v75, v87, v75
	v_add_f32_e64 v74, v88, v74
	v_add_f32_e64 v75, v89, v75
	v_pk_add_f32 v[74:75], v[90:91], v[74:75]
	s_nop 0
	v_pk_add_f32 v[74:75], v[92:93], v[74:75]
	s_nop 0
	v_pk_add_f32 v[74:75], v[94:95], v[74:75]
	s_nop 0
	v_pk_add_f32 v[74:75], v[96:97], v[74:75]
	s_nop 0
	v_pk_add_f32 v[74:75], v[98:99], v[74:75]
	s_nop 0
	v_pk_add_f32 v[68:69], v[68:69], v[74:75]
	s_nop 0
	v_pk_add_f32 v[68:69], v[70:71], v[68:69]
	s_nop 0
	v_pk_add_f32 v[68:69], v[72:73], v[68:69]
	s_nop 0
	v_pk_add_f32 v[68:69], v[230:231], v[68:69]
	s_nop 0
	v_pk_add_f32 v[68:69], v[232:233], v[68:69]
	s_nop 0
	v_pk_add_f32 v[68:69], v[234:235], v[68:69]
	s_nop 0
	v_pk_add_f32 v[68:69], v[236:237], v[68:69]
	s_nop 0
	v_pk_add_f32 v[68:69], v[82:83], v[68:69]
	s_nop 0
	v_add_f32_e32 v3, v68, v69
	ds_bpermute_b32 v68, v179, v3
	s_waitcnt lgkmcnt(0)
	v_add_f32_e32 v3, v3, v68
	v_fmac_f32_e32 v3, v217, v170

.LBB0_1455:
	v_sub_u32_e32 v68, v161, v221
	s_cmp_gt_i32 s39, s76
	v_cvt_f32_i32_e32 v69, v68
	s_cselect_b64 s[0:1], -1, 0
	s_and_b64 s[0:1], s[2:3], s[0:1]
	s_andn2_b64 vcc, exec, s[0:1]
	s_mov_b64 s[0:1], -1
	s_cbranch_vccz .LBB0_1459
	v_mov_b32_e32 v3, v157
	ds_read_b128 v[52:55], v220 offset:17920
	ds_read_b128 v[56:59], v220 offset:17952
	v_mul_f32_e64 v66, v69, -v3
	v_mov_b32_e32 v78, v3
	v_fma_f32 v38, 0, v3, v66
	v_fmamk_f32 v42, v3, 0x41000000, v66
	v_fmamk_f32 v46, v3, 0x41800000, v66
	v_fmamk_f32 v50, v3, 0x41c00000, v66
	v_pk_add_f32 v[36:37], v[2:3], v[38:39] op_sel_hi:[1,0]
	v_pk_fma_f32 v[38:39], v[78:79], s[64:65], v[38:39] op_sel_hi:[0,1,0]
	v_pk_add_f32 v[40:41], v[2:3], v[42:43] op_sel_hi:[1,0]
	v_pk_fma_f32 v[42:43], v[78:79], s[64:65], v[42:43] op_sel_hi:[0,1,0]
	v_pk_add_f32 v[44:45], v[2:3], v[46:47] op_sel_hi:[1,0]
	v_pk_fma_f32 v[46:47], v[78:79], s[64:65], v[46:47] op_sel_hi:[0,1,0]
	v_pk_add_f32 v[48:49], v[2:3], v[50:51] op_sel_hi:[1,0]
	v_pk_fma_f32 v[50:51], v[78:79], s[64:65], v[50:51] op_sel_hi:[0,1,0]
	v_fmamk_f32 v60, v3, 0x42200000, v66
	v_fmamk_f32 v62, v3, 0x42400000, v66
	s_waitcnt lgkmcnt(1)
	v_mfma_f32_32x32x16_bf16 v[36:51], v[52:55], v[100:103], v[36:51]
	v_cmp_gt_u32_e32 vcc, s47, v68
	s_waitcnt lgkmcnt(0)
	v_mfma_f32_32x32x16_bf16 v[36:51], v[56:59], v[104:107], v[36:51]
	ds_read_b128 v[52:55], v220 offset:17984
	ds_read_b128 v[56:59], v220 offset:18016
	ds_read_b128 v[70:73], v219 offset:17920
	ds_read_b128 v[74:77], v219 offset:17952
	s_waitcnt lgkmcnt(3)
	v_mfma_f32_32x32x16_bf16 v[36:51], v[52:55], v[108:111], v[36:51]
	v_fmamk_f32 v54, v3, 0x42000000, v66
	v_fmac_f32_e32 v66, 0x42600000, v3
	v_add_f32_e64 v52, v2, v54
	v_add_f32_e64 v53, v3, v54
	v_pk_fma_f32 v[54:55], v[78:79], s[64:65], v[54:55] op_sel_hi:[0,1,0]
	v_pk_add_f32 v[64:65], v[2:3], v[66:67] op_sel_hi:[1,0]
	v_pk_fma_f32 v[66:67], v[78:79], s[64:65], v[66:67] op_sel_hi:[0,1,0]
	s_waitcnt lgkmcnt(2)
	v_mfma_f32_32x32x16_bf16 v[36:51], v[56:59], v[112:115], v[36:51]
	v_add_f32_e64 v56, v2, v60
	v_add_f32_e64 v57, v3, v60
	v_fma_f32 v58, v78, s64, v60
	v_fma_f32 v59, v78, s65, v60
	v_add_f32_e64 v60, v2, v62
	v_add_f32_e64 v61, v3, v62
	v_pk_fma_f32 v[62:63], v[78:79], s[64:65], v[62:63] op_sel_hi:[0,1,0]
	v_add_u32_e32 v3, -1, v68
	s_nop 3
	v_cndmask_b32_e32 v88, v214, v36, vcc
	s_waitcnt lgkmcnt(1)
	v_mfma_f32_32x32x16_bf16 v[52:67], v[70:73], v[100:103], v[52:67]
	ds_read_b128 v[70:73], v219 offset:17984
	ds_read_b128 v[78:81], v219 offset:18016
	v_cmp_gt_u32_e32 vcc, s47, v3
	v_add_u32_e32 v36, -2, v68
	s_nop 0
	v_cndmask_b32_e32 v89, v214, v37, vcc
	v_cmp_gt_u32_e32 vcc, s47, v36
	v_add_u32_e32 v36, -3, v68
	s_waitcnt lgkmcnt(2)
	v_mfma_f32_32x32x16_bf16 v[52:67], v[74:77], v[104:107], v[52:67]
	v_cndmask_b32_e32 v94, v214, v38, vcc
	v_cmp_gt_u32_e32 vcc, s47, v36
	v_add_u32_e32 v36, -8, v68
	v_max3_f32 v3, v88, s97, v89
	v_cndmask_b32_e32 v95, v214, v39, vcc
	v_cmp_gt_u32_e32 vcc, s47, v36
	v_add_u32_e32 v36, -9, v68
	s_waitcnt lgkmcnt(1)
	v_mfma_f32_32x32x16_bf16 v[52:67], v[70:73], v[108:111], v[52:67]
	v_cndmask_b32_e32 v96, v214, v40, vcc
	v_cmp_gt_u32_e32 vcc, s47, v36
	v_add_u32_e32 v36, -10, v68
	v_max3_f32 v3, v3, v94, v95
	v_cndmask_b32_e32 v97, v214, v41, vcc
	v_cmp_gt_u32_e32 vcc, s47, v36
	v_add_u32_e32 v36, -11, v68
	s_waitcnt lgkmcnt(0)
	v_mfma_f32_32x32x16_bf16 v[52:67], v[78:81], v[112:115], v[52:67]
	v_cndmask_b32_e32 v98, v214, v42, vcc
	v_cmp_gt_u32_e32 vcc, s47, v36
	v_add_u32_e32 v36, -16, v68
	v_max3_f32 v3, v3, v96, v97
	v_cndmask_b32_e32 v99, v214, v43, vcc
	v_cmp_gt_u32_e32 vcc, s47, v36
	v_subrev_u32_e32 v36, 17, v68
	v_max3_f32 v3, v3, v98, v99
	v_cndmask_b32_e32 v170, v214, v44, vcc
	v_cmp_gt_u32_e32 vcc, s47, v36
	v_subrev_u32_e32 v36, 18, v68
	s_nop 0
	v_cndmask_b32_e32 v171, v214, v45, vcc
	v_cmp_gt_u32_e32 vcc, s47, v36
	v_subrev_u32_e32 v36, 19, v68
	v_max3_f32 v3, v3, v170, v171
	v_cndmask_b32_e32 v90, v214, v46, vcc
	v_cmp_gt_u32_e32 vcc, s47, v36
	v_subrev_u32_e32 v36, 24, v68
	s_nop 0
	v_cndmask_b32_e32 v91, v214, v47, vcc
	v_cmp_gt_u32_e32 vcc, s47, v36
	v_subrev_u32_e32 v36, 25, v68
	v_max3_f32 v3, v3, v90, v91
	v_cndmask_b32_e32 v92, v214, v48, vcc
	v_cmp_gt_u32_e32 vcc, s47, v36
	v_subrev_u32_e32 v36, 26, v68
	s_nop 0
	v_cndmask_b32_e32 v93, v214, v49, vcc
	v_cmp_gt_u32_e32 vcc, s47, v36
	v_subrev_u32_e32 v36, 27, v68
	v_max3_f32 v3, v3, v92, v93
	v_cndmask_b32_e32 v86, v214, v50, vcc
	v_cmp_gt_u32_e32 vcc, s47, v36
	v_subrev_u32_e32 v36, 32, v68
	s_nop 0
	v_cndmask_b32_e32 v87, v214, v51, vcc
	v_cmp_gt_u32_e32 vcc, s47, v36
	v_subrev_u32_e32 v36, 33, v68
	v_max3_f32 v3, v3, v86, v87
	v_cndmask_b32_e32 v76, v214, v52, vcc
	v_cmp_gt_u32_e32 vcc, s47, v36
	v_subrev_u32_e32 v36, 34, v68
	s_nop 0
	v_cndmask_b32_e32 v77, v214, v53, vcc
	v_cmp_gt_u32_e32 vcc, s47, v36
	v_subrev_u32_e32 v36, 35, v68
	v_max3_f32 v3, v3, v76, v77
	v_cndmask_b32_e32 v78, v214, v54, vcc
	v_cmp_gt_u32_e32 vcc, s47, v36
	v_subrev_u32_e32 v36, 40, v68
	s_nop 0
	v_cndmask_b32_e32 v79, v214, v55, vcc
	v_cmp_gt_u32_e32 vcc, s47, v36
	v_subrev_u32_e32 v36, 41, v68
	v_max3_f32 v3, v3, v78, v79
	v_cndmask_b32_e32 v80, v214, v56, vcc
	v_cmp_gt_u32_e32 vcc, s47, v36
	v_subrev_u32_e32 v36, 42, v68
	s_nop 0
	v_cndmask_b32_e32 v81, v214, v57, vcc
	v_cmp_gt_u32_e32 vcc, s47, v36
	v_subrev_u32_e32 v36, 43, v68
	v_max3_f32 v3, v3, v80, v81
	v_cndmask_b32_e32 v82, v214, v58, vcc
	v_cmp_gt_u32_e32 vcc, s47, v36
	v_subrev_u32_e32 v36, 48, v68
	s_nop 0
	v_cndmask_b32_e32 v83, v214, v59, vcc
	v_cmp_gt_u32_e32 vcc, s47, v36
	v_subrev_u32_e32 v36, 49, v68
	v_max3_f32 v3, v3, v82, v83
	v_cndmask_b32_e32 v84, v214, v60, vcc
	v_cmp_gt_u32_e32 vcc, s47, v36
	v_subrev_u32_e32 v36, 50, v68
	s_nop 0
	v_cndmask_b32_e32 v85, v214, v61, vcc
	v_cmp_gt_u32_e32 vcc, s47, v36
	v_subrev_u32_e32 v36, 51, v68
	v_max3_f32 v3, v3, v84, v85
	v_cndmask_b32_e32 v74, v214, v62, vcc
	v_cmp_gt_u32_e32 vcc, s47, v36
	v_subrev_u32_e32 v36, 56, v68
	s_nop 0
	v_cndmask_b32_e32 v75, v214, v63, vcc
	v_cmp_gt_u32_e32 vcc, s47, v36
	v_subrev_u32_e32 v36, 57, v68
	v_max3_f32 v3, v3, v74, v75
	v_cndmask_b32_e32 v70, v214, v64, vcc
	v_cmp_gt_u32_e32 vcc, s47, v36
	v_subrev_u32_e32 v36, 58, v68
	s_nop 0
	v_cndmask_b32_e32 v71, v214, v65, vcc
	v_cmp_gt_u32_e32 vcc, s47, v36
	v_subrev_u32_e32 v36, 59, v68
	v_max3_f32 v3, v3, v70, v71
	v_cndmask_b32_e32 v72, v214, v66, vcc
	v_cmp_gt_u32_e32 vcc, s47, v36
	s_nop 1
	v_cndmask_b32_e32 v73, v214, v67, vcc
	v_max3_f32 v3, v3, v72, v73
	ds_bpermute_b32 v36, v179, v3
	s_nop 3
	s_waitcnt lgkmcnt(0)
	v_max_f32_e32 v36, v36, v36
	v_max_f32_e32 v3, v3, v36
	v_max3_f32 v132, v218, v3, s46
	v_sub_f32_e32 v3, v218, v132
	v_exp_f32_e32 v68, v3
	s_nop 2
	v_cmp_eq_f32_e32 vcc, 1.0, v68
	s_cmp_eq_u64 vcc, exec
	s_nop 8
	s_cbranch_scc1 .LBB0_1458
	v_pk_mul_f32 v[34:35], v[34:35], v[68:69] op_sel_hi:[1,0]
	v_pk_mul_f32 v[32:33], v[32:33], v[68:69] op_sel_hi:[1,0]
	v_pk_mul_f32 v[30:31], v[30:31], v[68:69] op_sel_hi:[1,0]
	v_pk_mul_f32 v[28:29], v[28:29], v[68:69] op_sel_hi:[1,0]
	v_pk_mul_f32 v[26:27], v[26:27], v[68:69] op_sel_hi:[1,0]
	v_pk_mul_f32 v[24:25], v[24:25], v[68:69] op_sel_hi:[1,0]
	v_pk_mul_f32 v[22:23], v[22:23], v[68:69] op_sel_hi:[1,0]
	v_pk_mul_f32 v[20:21], v[20:21], v[68:69] op_sel_hi:[1,0]
	v_pk_mul_f32 v[18:19], v[18:19], v[68:69] op_sel_hi:[1,0]
	v_pk_mul_f32 v[16:17], v[16:17], v[68:69] op_sel_hi:[1,0]
	v_pk_mul_f32 v[14:15], v[14:15], v[68:69] op_sel_hi:[1,0]
	v_pk_mul_f32 v[12:13], v[12:13], v[68:69] op_sel_hi:[1,0]
	v_pk_mul_f32 v[10:11], v[10:11], v[68:69] op_sel_hi:[1,0]
	v_pk_mul_f32 v[8:9], v[8:9], v[68:69] op_sel_hi:[1,0]
	v_pk_mul_f32 v[6:7], v[6:7], v[68:69] op_sel_hi:[1,0]
	v_pk_mul_f32 v[4:5], v[4:5], v[68:69] op_sel_hi:[1,0]
.LBB0_1458:
	v_pk_add_f32 v[94:95], v[94:95], v[132:133] op_sel_hi:[1,0] neg_lo:[0,1] neg_hi:[0,1]
	v_lshl_add_u32 v3, v136, 1, s38
	v_exp_f32_e32 v230, v94
	v_exp_f32_e32 v231, v95
	v_pk_add_f32 v[94:95], v[96:97], v[132:133] op_sel_hi:[1,0] neg_lo:[0,1] neg_hi:[0,1]
	v_pk_add_f32 v[88:89], v[88:89], v[132:133] op_sel_hi:[1,0] neg_lo:[0,1] neg_hi:[0,1]
	v_exp_f32_e32 v232, v94
	v_exp_f32_e32 v233, v95
	v_pk_add_f32 v[94:95], v[98:99], v[132:133] op_sel_hi:[1,0] neg_lo:[0,1] neg_hi:[0,1]
	v_exp_f32_e32 v88, v88
	v_exp_f32_e32 v98, v94
	v_add_u32_e32 v94, v3, v190
	v_add_u32_e32 v186, 0x6800, v94
	v_exp_f32_e32 v99, v95
	ds_read2_b64 v[94:97], v186 offset0:64 offset1:66
	v_add_u32_e32 v3, v3, v191
	v_add_u32_e32 v3, 0x6800, v3
	ds_read2_b64 v[226:229], v3 offset0:64 offset1:66
	v_exp_f32_e32 v89, v89
	v_pk_add_f32 v[90:91], v[90:91], v[132:133] op_sel_hi:[1,0] neg_lo:[0,1] neg_hi:[0,1]
	v_cvt_pk_bf16_f32 v223, v230, v231
	v_exp_f32_e32 v234, v90
	v_exp_f32_e32 v235, v91
	v_pk_add_f32 v[90:91], v[92:93], v[132:133] op_sel_hi:[1,0] neg_lo:[0,1] neg_hi:[0,1]
	v_cvt_pk_bf16_f32 v222, v88, v89
	v_cvt_pk_bf16_f32 v224, v232, v233
	v_cvt_pk_bf16_f32 v225, v98, v99
	v_exp_f32_e32 v236, v90
	v_exp_f32_e32 v237, v91
	ds_read2_b64 v[90:93], v186 offset0:68 offset1:70
	s_waitcnt lgkmcnt(2)
	v_mfma_f32_32x32x16_bf16 v[20:35], v[94:97], v[222:225], v[20:35]
	v_add_f32_e64 v170, v170, -v132
	v_add_f32_e64 v171, v171, -v132
	v_add_f32_e64 v86, v86, -v132
	v_add_f32_e64 v87, v87, -v132
	v_exp_f32_e32 v170, v170
	v_exp_f32_e32 v171, v171
	v_cvt_pk_bf16_f32 v95, v234, v235
	v_cvt_pk_bf16_f32 v96, v236, v237
	v_cvt_pk_bf16_f32 v94, v170, v171
	s_waitcnt lgkmcnt(1)
	v_mfma_f32_32x32x16_bf16 v[4:19], v[226:229], v[222:225], v[4:19]
	v_exp_f32_e32 v222, v86
	v_exp_f32_e32 v223, v87
	s_nop 0
	v_cvt_pk_bf16_f32 v97, v222, v223
	s_waitcnt lgkmcnt(0)
	s_nop 0
	v_mfma_f32_32x32x16_bf16 v[20:35], v[90:93], v[94:97], v[20:35]
	ds_read2_b64 v[90:93], v3 offset0:68 offset1:70
	s_waitcnt lgkmcnt(0)
	v_mfma_f32_32x32x16_bf16 v[4:19], v[90:93], v[94:97], v[4:19]
	v_add_f32_e64 v76, v76, -v132
	v_add_f32_e64 v77, v77, -v132
	v_add_f32_e64 v74, v74, -v132
	v_add_f32_e64 v75, v75, -v132
	v_exp_f32_e32 v90, v76
	v_exp_f32_e32 v91, v77
	v_pk_add_f32 v[76:77], v[78:79], v[132:133] op_sel_hi:[1,0] neg_lo:[0,1] neg_hi:[0,1]
	v_pk_add_f32 v[70:71], v[70:71], v[132:133] op_sel_hi:[1,0] neg_lo:[0,1] neg_hi:[0,1]
	v_exp_f32_e32 v92, v76
	v_exp_f32_e32 v93, v77
	v_pk_add_f32 v[76:77], v[80:81], v[132:133] op_sel_hi:[1,0] neg_lo:[0,1] neg_hi:[0,1]
	v_pk_add_f32 v[80:81], v[84:85], v[132:133] op_sel_hi:[1,0] neg_lo:[0,1] neg_hi:[0,1]
	v_exp_f32_e32 v94, v76
	v_exp_f32_e32 v95, v77
	v_pk_add_f32 v[76:77], v[82:83], v[132:133] op_sel_hi:[1,0] neg_lo:[0,1] neg_hi:[0,1]
	ds_read2_b64 v[84:87], v3 offset0:72 offset1:74
	v_exp_f32_e32 v96, v76
	v_exp_f32_e32 v97, v77
	ds_read2_b64 v[76:79], v186 offset0:72 offset1:74
	v_exp_f32_e32 v224, v80
	v_exp_f32_e32 v225, v81
	v_cvt_pk_bf16_f32 v80, v90, v91
	v_cvt_pk_bf16_f32 v81, v92, v93
	v_cvt_pk_bf16_f32 v82, v94, v95
	v_cvt_pk_bf16_f32 v83, v96, v97
	v_exp_f32_e32 v226, v74
	v_exp_f32_e32 v227, v75
	v_exp_f32_e32 v228, v70
	v_exp_f32_e32 v229, v71
	v_pk_add_f32 v[74:75], v[72:73], v[132:133] op_sel_hi:[1,0] neg_lo:[0,1] neg_hi:[0,1]
	ds_read2_b64 v[70:73], v186 offset0:76 offset1:78
	s_waitcnt lgkmcnt(1)
	v_mfma_f32_32x32x16_bf16 v[20:35], v[76:79], v[80:83], v[20:35]
	v_cvt_pk_bf16_f32 v78, v224, v225
	v_cvt_pk_bf16_f32 v79, v226, v227
	s_mov_b64 s[0:1], 0
	v_mfma_f32_32x32x16_bf16 v[4:19], v[84:87], v[80:83], v[4:19]
	v_exp_f32_e32 v82, v74
	v_exp_f32_e32 v83, v75
	v_cvt_pk_bf16_f32 v80, v228, v229
	ds_read2_b64 v[74:77], v3 offset0:76 offset1:78
	v_cvt_pk_bf16_f32 v81, v82, v83
	s_waitcnt lgkmcnt(1)
	s_nop 0
	v_mfma_f32_32x32x16_bf16 v[20:35], v[70:73], v[78:81], v[20:35]
	v_add_f32_e64 v70, v88, 0
	v_add_f32_e64 v71, v89, 0
	v_add_f32_e64 v70, v230, v70
	v_add_f32_e64 v71, v231, v71
	v_add_f32_e64 v70, v232, v70
	v_add_f32_e64 v71, v233, v71
	v_pk_add_f32 v[70:71], v[98:99], v[70:71]
	s_waitcnt lgkmcnt(0)
	v_mfma_f32_32x32x16_bf16 v[4:19], v[74:77], v[78:81], v[4:19]
	v_add_f32_e64 v70, v170, v70
	v_add_f32_e64 v71, v171, v71
	v_add_f32_e64 v70, v234, v70
	v_add_f32_e64 v71, v235, v71
	v_add_f32_e64 v70, v236, v70
	v_add_f32_e64 v71, v237, v71
	v_pk_add_f32 v[70:71], v[222:223], v[70:71]
	s_nop 0
	v_pk_add_f32 v[70:71], v[90:91], v[70:71]
	s_nop 0
	v_pk_add_f32 v[70:71], v[92:93], v[70:71]
	s_nop 0
	v_pk_add_f32 v[70:71], v[94:95], v[70:71]
	s_nop 0
	v_pk_add_f32 v[70:71], v[96:97], v[70:71]
	s_nop 0
	v_pk_add_f32 v[70:71], v[224:225], v[70:71]
	s_nop 0
	v_pk_add_f32 v[70:71], v[226:227], v[70:71]
	s_nop 0
	v_pk_add_f32 v[70:71], v[228:229], v[70:71]
	s_nop 0
	v_pk_add_f32 v[70:71], v[82:83], v[70:71]
	s_nop 0
	v_add_f32_e32 v3, v70, v71
	ds_bpermute_b32 v70, v179, v3
	s_waitcnt lgkmcnt(0)
	v_add_f32_e32 v3, v3, v70
	v_fmac_f32_e32 v3, v217, v68

.LBB0_1462:
	v_add_u32_e32 v3, v165, v196
	v_pk_add_f32 v[52:53], v[52:53], v[132:133] op_sel_hi:[1,0] neg_lo:[0,1] neg_hi:[0,1]
	v_pk_add_f32 v[54:55], v[54:55], v[132:133] op_sel_hi:[1,0] neg_lo:[0,1] neg_hi:[0,1]
	v_pk_add_f32 v[56:57], v[56:57], v[132:133] op_sel_hi:[1,0] neg_lo:[0,1] neg_hi:[0,1]
	v_pk_add_f32 v[58:59], v[58:59], v[132:133] op_sel_hi:[1,0] neg_lo:[0,1] neg_hi:[0,1]
	v_add_u32_e32 v69, v3, v190
	v_exp_f32_e32 v52, v52
	v_exp_f32_e32 v53, v53
	v_exp_f32_e32 v54, v54
	v_exp_f32_e32 v55, v55
	v_exp_f32_e32 v56, v56
	v_exp_f32_e32 v57, v57
	v_exp_f32_e32 v58, v58
	v_exp_f32_e32 v59, v59
	v_add_u32_e32 v69, 0x6800, v69
	ds_read2_b64 v[74:77], v69 offset0:64 offset1:66
	ds_read2_b64 v[78:81], v69 offset0:68 offset1:70
	v_add_u32_e32 v3, v3, v191
	v_cvt_pk_bf16_f32 v70, v52, v53
	v_cvt_pk_bf16_f32 v71, v54, v55
	v_cvt_pk_bf16_f32 v72, v56, v57
	v_cvt_pk_bf16_f32 v73, v58, v59
	v_add_u32_e32 v3, 0x6800, v3
	v_pk_add_f32 v[60:61], v[60:61], v[132:133] op_sel_hi:[1,0] neg_lo:[0,1] neg_hi:[0,1]
	s_waitcnt lgkmcnt(1)
	v_mfma_f32_32x32x16_bf16 v[20:35], v[74:77], v[70:73], v[20:35]
	ds_read2_b64 v[74:77], v3 offset0:64 offset1:66
	ds_read2_b64 v[82:85], v3 offset0:68 offset1:70
	v_add_f32_e64 v62, v62, -v132
	v_add_f32_e64 v63, v63, -v132
	v_add_f32_e64 v64, v64, -v132
	v_add_f32_e64 v65, v65, -v132
	v_pk_add_f32 v[66:67], v[66:67], v[132:133] op_sel_hi:[1,0] neg_lo:[0,1] neg_hi:[0,1]
	v_exp_f32_e32 v60, v60
	v_exp_f32_e32 v61, v61
	v_exp_f32_e32 v62, v62
	s_waitcnt lgkmcnt(1)
	v_mfma_f32_32x32x16_bf16 v[4:19], v[74:77], v[70:73], v[4:19]
	v_exp_f32_e32 v63, v63
	v_exp_f32_e32 v64, v64
	v_exp_f32_e32 v65, v65
	v_exp_f32_e32 v66, v66
	v_exp_f32_e32 v67, v67
	v_cvt_pk_bf16_f32 v70, v60, v61
	v_cvt_pk_bf16_f32 v71, v62, v63
	v_cvt_pk_bf16_f32 v72, v64, v65
	v_cvt_pk_bf16_f32 v73, v66, v67
	s_nop 1
	v_mfma_f32_32x32x16_bf16 v[20:35], v[78:81], v[70:73], v[20:35]
	s_waitcnt lgkmcnt(0)
	v_mfma_f32_32x32x16_bf16 v[4:19], v[82:85], v[70:73], v[4:19]
	v_add_f32_e64 v42, v42, -v132
	v_add_f32_e64 v43, v43, -v132
	v_add_f32_e64 v36, v36, -v132
	v_add_f32_e64 v37, v37, -v132
	v_add_f32_e64 v38, v38, -v132
	v_add_f32_e64 v39, v39, -v132
	v_pk_add_f32 v[40:41], v[40:41], v[132:133] op_sel_hi:[1,0] neg_lo:[0,1] neg_hi:[0,1]
	v_exp_f32_e32 v78, v42
	v_exp_f32_e32 v79, v43
	v_pk_add_f32 v[42:43], v[44:45], v[132:133] op_sel_hi:[1,0] neg_lo:[0,1] neg_hi:[0,1]
	v_exp_f32_e32 v36, v36
	v_exp_f32_e32 v37, v37
	v_exp_f32_e32 v38, v38
	v_exp_f32_e32 v39, v39
	v_exp_f32_e32 v40, v40
	v_exp_f32_e32 v41, v41
	v_exp_f32_e32 v80, v42
	v_exp_f32_e32 v81, v43
	v_pk_add_f32 v[42:43], v[46:47], v[132:133] op_sel_hi:[1,0] neg_lo:[0,1] neg_hi:[0,1]
	v_cvt_pk_bf16_f32 v44, v40, v41
	v_exp_f32_e32 v82, v42
	v_exp_f32_e32 v83, v43
	v_pk_add_f32 v[42:43], v[48:49], v[132:133] op_sel_hi:[1,0] neg_lo:[0,1] neg_hi:[0,1]
	ds_read2_b64 v[46:49], v69 offset0:72 offset1:74
	ds_read2_b64 v[70:73], v69 offset0:76 offset1:78
	v_exp_f32_e32 v84, v42
	v_exp_f32_e32 v85, v43
	v_pk_add_f32 v[42:43], v[50:51], v[132:133] op_sel_hi:[1,0] neg_lo:[0,1] neg_hi:[0,1]
	v_cvt_pk_bf16_f32 v45, v78, v79
	v_exp_f32_e32 v50, v42
	v_exp_f32_e32 v51, v43
	v_cvt_pk_bf16_f32 v42, v36, v37
	v_cvt_pk_bf16_f32 v43, v38, v39
	s_waitcnt lgkmcnt(1)
	s_nop 0
	v_mfma_f32_32x32x16_bf16 v[20:35], v[46:49], v[42:45], v[20:35]
	ds_read2_b64 v[46:49], v3 offset0:72 offset1:74
	ds_read2_b64 v[74:77], v3 offset0:76 offset1:78
	s_waitcnt lgkmcnt(1)
	v_mfma_f32_32x32x16_bf16 v[4:19], v[46:49], v[42:45], v[4:19]
	v_cvt_pk_bf16_f32 v42, v80, v81
	v_cvt_pk_bf16_f32 v43, v82, v83
	v_cvt_pk_bf16_f32 v44, v84, v85
	v_cvt_pk_bf16_f32 v45, v50, v51
	s_nop 1
	v_mfma_f32_32x32x16_bf16 v[20:35], v[70:73], v[42:45], v[20:35]
	s_waitcnt lgkmcnt(0)
	v_mfma_f32_32x32x16_bf16 v[4:19], v[74:77], v[42:45], v[4:19]
	v_add_f32_e64 v42, v52, 0
	v_add_f32_e64 v43, v53, 0
	v_add_f32_e64 v42, v54, v42
	v_add_f32_e64 v43, v55, v43
	v_add_f32_e64 v42, v56, v42
	v_add_f32_e64 v43, v57, v43
	v_pk_add_f32 v[42:43], v[58:59], v[42:43]
	s_nop 0
	v_pk_add_f32 v[42:43], v[60:61], v[42:43]
	s_nop 0
	v_pk_add_f32 v[42:43], v[62:63], v[42:43]
	s_nop 0
	v_pk_add_f32 v[42:43], v[64:65], v[42:43]
	s_nop 0
	v_pk_add_f32 v[42:43], v[66:67], v[42:43]
	s_nop 0
	v_pk_add_f32 v[36:37], v[36:37], v[42:43]
	s_nop 0
	v_pk_add_f32 v[36:37], v[38:39], v[36:37]
	s_nop 0
	v_pk_add_f32 v[36:37], v[40:41], v[36:37]
	s_nop 0
	v_pk_add_f32 v[36:37], v[78:79], v[36:37]
	s_nop 0
	v_pk_add_f32 v[36:37], v[80:81], v[36:37]
	s_nop 0
	v_pk_add_f32 v[36:37], v[82:83], v[36:37]
	s_nop 0
	v_pk_add_f32 v[36:37], v[84:85], v[36:37]
	s_nop 0
	v_pk_add_f32 v[36:37], v[50:51], v[36:37]
	s_nop 0
	v_add_f32_e32 v3, v36, v37
	ds_bpermute_b32 v36, v179, v3
	s_waitcnt lgkmcnt(0)
	v_add_f32_e32 v3, v3, v36
	s_nop 0
	v_fmac_f32_e32 v3, v217, v68
	s_nop 6
	s_branch .LBB0_1464

.LBB0_1464:
	s_nop 1
	v_mov_b32_e32 v218, v132
	v_mov_b32_e32 v217, v3
	s_nop 13
